# diff-attention epilogue (both instances): 15 serialized store->load->vmcnt(0) round trips replaced by a 4-deep subln prefetch ring with counted vmcnt
# speedup vs baseline: 1.0526x; 1.0070x over previous
.LBB0_854:
	s_cmpk_gt_u32 s10, 0xff
	s_waitcnt lgkmcnt(0)
	s_barrier
	s_cbranch_scc1 .LBB0_829
	s_lshl_b32 s3, s10, 8
	v_lshl_add_u32 v68, v64, 2, 0
	s_and_b32 s4, s3, 0xc000
	v_add_u32_e32 v69, s4, v68
	ds_read2st64_b32 v[96:97], v69 offset1:1
	ds_read2st64_b32 v[98:99], v69 offset0:2 offset1:3
	ds_read2st64_b32 v[104:105], v69 offset0:4 offset1:5
	ds_read2st64_b32 v[108:109], v69 offset0:6 offset1:7
	ds_read2st64_b32 v[112:113], v69 offset0:8 offset1:9
	ds_read2st64_b32 v[114:115], v69 offset0:10 offset1:11
	ds_read2st64_b32 v[120:121], v69 offset0:12 offset1:13
	ds_read2st64_b32 v[124:125], v69 offset0:14 offset1:15
	ds_read2st64_b32 v[126:127], v69 offset0:16 offset1:17
	ds_read2st64_b32 v[122:123], v69 offset0:18 offset1:19
	ds_read2st64_b32 v[128:129], v69 offset0:20 offset1:21
	ds_read2st64_b32 v[134:135], v69 offset0:22 offset1:23
	ds_read2st64_b32 v[130:131], v69 offset0:24 offset1:25
	ds_read2st64_b32 v[138:139], v69 offset0:26 offset1:27
	ds_read2st64_b32 v[142:143], v69 offset0:28 offset1:29
	ds_read2st64_b32 v[166:167], v69 offset0:30 offset1:31
	ds_read2st64_b32 v[136:137], v69 offset0:32 offset1:33
	ds_read2st64_b32 v[148:149], v69 offset0:34 offset1:35
	ds_read2st64_b32 v[150:151], v69 offset0:36 offset1:37
	ds_read2st64_b32 v[152:153], v69 offset0:38 offset1:39
	ds_read2st64_b32 v[102:103], v69 offset0:40 offset1:41
	ds_read2st64_b32 v[106:107], v69 offset0:42 offset1:43
	ds_read2st64_b32 v[90:91], v69 offset0:44 offset1:45
	ds_read2st64_b32 v[92:93], v69 offset0:46 offset1:47
	ds_read2st64_b32 v[86:87], v69 offset0:48 offset1:49
	ds_read2st64_b32 v[88:89], v69 offset0:50 offset1:51
	ds_read2st64_b32 v[82:83], v69 offset0:52 offset1:53
	ds_read2st64_b32 v[84:85], v69 offset0:54 offset1:55
	ds_read2st64_b32 v[78:79], v69 offset0:56 offset1:57
	ds_read2st64_b32 v[80:81], v69 offset0:58 offset1:59
	ds_read2st64_b32 v[64:65], v69 offset0:60 offset1:61
	s_or_b32 s3, s3, 0x3f00
	s_lshl_b32 s2, s17, 7
	s_movk_i32 s4, 0x1400
	s_lshl_b32 s40, s2, 1
	s_waitcnt lgkmcnt(0)
	v_pk_mul_f32 v[64:65], v[144:145], v[64:65]
	v_pk_mul_f32 v[96:97], v[144:145], v[96:97]
	v_pk_fma_f32 v[66:67], v[12:13], v[72:73], v[64:65] op_sel_hi:[1,0,1] neg_lo:[0,0,1] neg_hi:[0,0,1]
	v_add_u32_e32 v13, s3, v68
	ds_read_b32 v12, v69 offset:15872
	ds_read_b32 v13, v13
	v_pk_mul_f32 v[98:99], v[144:145], v[98:99]
	v_pk_mul_f32 v[104:105], v[144:145], v[104:105]
	v_pk_mul_f32 v[108:109], v[144:145], v[108:109]
	v_pk_mul_f32 v[112:113], v[144:145], v[112:113]
	s_waitcnt lgkmcnt(0)
	v_pk_mul_f32 v[12:13], v[144:145], v[12:13]
	v_pk_mul_f32 v[114:115], v[144:145], v[114:115]
	v_pk_fma_f32 v[64:65], v[14:15], v[72:73], v[12:13] op_sel_hi:[1,0,1] neg_lo:[0,0,1] neg_hi:[0,0,1]
	v_mov_b64_e32 v[14:15], s[14:15]
	v_mad_u64_u32 v[14:15], s[2:3], v174, s4, v[14:15]
	v_mov_b32_e32 v68, v15
	v_mad_u64_u32 v[68:69], s[2:3], v173, s4, v[68:69]
	v_mov_b32_e32 v15, v68
	v_lshrrev_b32_e32 v68, 3, v172
	v_and_b32_e32 v73, 4, v68
	v_lshl_add_u64 v[12:13], v[146:147], 0, s[40:41]
	v_lshlrev_b32_e32 v192, 1, v73
	v_lshl_add_u64 v[12:13], v[12:13], 0, v[192:193]
	s_mov_b64 s[2:3], 0x1000
	v_lshl_add_u64 v[68:69], v[12:13], 0, s[2:3]
	v_add_co_u32_e32 v12, vcc, s5, v12
	v_pk_fma_f32 v[96:97], v[48:49], v[72:73], v[96:97] op_sel_hi:[1,0,1] neg_lo:[0,0,1] neg_hi:[0,0,1]
	s_nop 0
	v_addc_co_u32_e32 v13, vcc, 0, v13, vcc
	flat_load_dwordx2 v[100:101], v[12:13]
	flat_load_dwordx2 v[162:163], v[68:69] offset:16
	flat_load_dwordx2 v[140:141], v[68:69] offset:32
	flat_load_dwordx2 v[132:133], v[68:69] offset:48
	flat_load_dwordx2 v[180:181], v[68:69] offset:64
	flat_load_dwordx2 v[186:187], v[68:69] offset:80
	flat_load_dwordx2 v[184:185], v[68:69] offset:96
	flat_load_dwordx2 v[178:179], v[68:69] offset:112
	flat_load_dwordx2 v[146:147], v[68:69] offset:128
	flat_load_dwordx2 v[168:169], v[68:69] offset:144
	flat_load_dwordx2 v[160:161], v[68:69] offset:160
	flat_load_dwordx2 v[154:155], v[68:69] offset:176
	flat_load_dwordx2 v[118:119], v[68:69] offset:192
	flat_load_dwordx2 v[94:95], v[68:69] offset:208
	flat_load_dwordx2 v[70:71], v[68:69] offset:224
	s_nop 0
	flat_load_dwordx2 v[68:69], v[68:69] offset:240
	v_lshlrev_b32_e32 v205, 2, v73
	v_pk_fma_f32 v[50:51], v[50:51], v[72:73], v[98:99] op_sel_hi:[1,0,1] neg_lo:[0,0,1] neg_hi:[0,0,1]
	v_pk_mul_f32 v[120:121], v[144:145], v[120:121]
	v_pk_mul_f32 v[124:125], v[144:145], v[124:125]
	v_pk_mul_f32 v[122:123], v[144:145], v[122:123]
	v_pk_mul_f32 v[80:81], v[144:145], v[80:81]
	v_pk_mul_f32 v[78:79], v[144:145], v[78:79]
	v_pk_mul_f32 v[116:117], v[96:97], v[96:97]
	v_lshl_add_u64 v[156:157], v[14:15], 0, s[40:41]
	global_load_dwordx4 v[12:15], v205, s[0:1]
	global_load_dwordx4 v[240:243], v205, s[0:1] offset:32
	global_load_dwordx4 v[244:247], v205, s[0:1] offset:64
	global_load_dwordx4 v[248:251], v205, s[0:1] offset:96
	v_pk_mul_f32 v[110:111], v[50:51], v[50:51]
	v_pk_mul_f32 v[74:75], v[66:67], v[66:67]
	v_pk_mul_f32 v[76:77], v[64:65], v[64:65]
	s_mov_b32 s2, 0x800000
	s_waitcnt vmcnt(0) lgkmcnt(0)
	v_lshlrev_b32_e32 v48, 16, v100
	v_mul_f32_e32 v73, 0xbfb8aa3b, v48
	v_exp_f32_e32 v73, v73
	v_and_b32_e32 v49, 0xffff0000, v100
	v_add_f32_e32 v73, 1.0, v73
	v_rcp_f32_e32 v98, v73
	v_mul_f32_e32 v73, 0xbfb8aa3b, v49
	v_exp_f32_e32 v73, v73
	s_nop 0
	v_add_f32_e32 v73, 1.0, v73
	v_rcp_f32_e32 v99, v73
	s_nop 0
	v_pk_mul_f32 v[98:99], v[98:99], v[48:49]
	v_lshlrev_b32_e32 v48, 16, v101
	v_mul_f32_e32 v73, 0xbfb8aa3b, v48
	v_exp_f32_e32 v73, v73
	v_and_b32_e32 v49, 0xffff0000, v101
	v_add_f32_e32 v73, 1.0, v73
	v_rcp_f32_e32 v100, v73
	v_mul_f32_e32 v73, 0xbfb8aa3b, v49
	v_exp_f32_e32 v73, v73
	s_nop 0
	v_add_f32_e32 v73, 1.0, v73
	v_pk_fma_f32 v[52:53], v[52:53], v[72:73], v[104:105] op_sel_hi:[1,0,1] neg_lo:[0,0,1] neg_hi:[0,0,1]
	v_lshlrev_b32_e32 v104, 16, v162
	v_rcp_f32_e32 v101, v73
	v_pk_fma_f32 v[54:55], v[54:55], v[72:73], v[108:109] op_sel_hi:[1,0,1] neg_lo:[0,0,1] neg_hi:[0,0,1]
	v_mul_f32_e32 v73, 0xbfb8aa3b, v104
	v_exp_f32_e32 v73, v73
	v_and_b32_e32 v105, 0xffff0000, v162
	v_pk_mul_f32 v[158:159], v[52:53], v[52:53]
	v_pk_mul_f32 v[100:101], v[100:101], v[48:49]
	v_add_f32_e32 v73, 1.0, v73
	v_rcp_f32_e32 v108, v73
	v_mul_f32_e32 v73, 0xbfb8aa3b, v105
	v_exp_f32_e32 v73, v73
	v_lshl_add_u64 v[48:49], v[156:157], 0, v[192:193]
	v_pk_mul_f32 v[156:157], v[54:55], v[54:55]
	v_add_f32_e32 v73, 1.0, v73
	v_rcp_f32_e32 v109, v73
	s_nop 0
	v_pk_mul_f32 v[104:105], v[108:109], v[104:105]
	v_lshlrev_b32_e32 v108, 16, v163
	v_mul_f32_e32 v73, 0xbfb8aa3b, v108
	v_exp_f32_e32 v73, v73
	v_and_b32_e32 v109, 0xffff0000, v163
	v_add_f32_e32 v73, 1.0, v73
	v_rcp_f32_e32 v162, v73
	v_mul_f32_e32 v73, 0xbfb8aa3b, v109
	v_exp_f32_e32 v73, v73
	s_nop 0
	v_add_f32_e32 v73, 1.0, v73
	v_pk_fma_f32 v[56:57], v[56:57], v[72:73], v[112:113] op_sel_hi:[1,0,1] neg_lo:[0,0,1] neg_hi:[0,0,1]
	v_lshlrev_b32_e32 v112, 16, v140
	v_rcp_f32_e32 v163, v73
	v_pk_fma_f32 v[58:59], v[58:59], v[72:73], v[114:115] op_sel_hi:[1,0,1] neg_lo:[0,0,1] neg_hi:[0,0,1]
	v_mul_f32_e32 v73, 0xbfb8aa3b, v112
	v_exp_f32_e32 v73, v73
	v_and_b32_e32 v113, 0xffff0000, v140
	v_pk_mul_f32 v[164:165], v[56:57], v[56:57]
	v_pk_mul_f32 v[108:109], v[162:163], v[108:109]
	v_add_f32_e32 v73, 1.0, v73
	v_rcp_f32_e32 v114, v73
	v_mul_f32_e32 v73, 0xbfb8aa3b, v113
	v_exp_f32_e32 v73, v73
	v_pk_mul_f32 v[162:163], v[58:59], v[58:59]
	v_add_f32_e32 v73, 1.0, v73
	v_rcp_f32_e32 v115, v73
	s_nop 0
	v_pk_mul_f32 v[112:113], v[114:115], v[112:113]
	v_lshlrev_b32_e32 v114, 16, v141
	v_mul_f32_e32 v73, 0xbfb8aa3b, v114
	v_exp_f32_e32 v73, v73
	v_and_b32_e32 v115, 0xffff0000, v141
	v_add_f32_e32 v73, 1.0, v73
	v_rcp_f32_e32 v140, v73
	v_mul_f32_e32 v73, 0xbfb8aa3b, v115
	v_exp_f32_e32 v73, v73
	s_nop 0
	v_add_f32_e32 v73, 1.0, v73
	v_pk_fma_f32 v[60:61], v[60:61], v[72:73], v[120:121] op_sel_hi:[1,0,1] neg_lo:[0,0,1] neg_hi:[0,0,1]
	v_lshlrev_b32_e32 v120, 16, v132
	v_rcp_f32_e32 v141, v73
	v_pk_fma_f32 v[62:63], v[62:63], v[72:73], v[124:125] op_sel_hi:[1,0,1] neg_lo:[0,0,1] neg_hi:[0,0,1]
	v_mul_f32_e32 v73, 0xbfb8aa3b, v120
	v_exp_f32_e32 v73, v73
	v_and_b32_e32 v121, 0xffff0000, v132
	v_pk_mul_f32 v[114:115], v[140:141], v[114:115]
	v_pk_mul_f32 v[172:173], v[60:61], v[60:61]
	v_add_f32_e32 v73, 1.0, v73
	v_rcp_f32_e32 v124, v73
	v_mul_f32_e32 v73, 0xbfb8aa3b, v121
	v_exp_f32_e32 v73, v73
	v_pk_mul_f32 v[170:171], v[62:63], v[62:63]
	v_add_f32_e32 v73, 1.0, v73
	v_rcp_f32_e32 v125, v73
	s_nop 0
	v_pk_mul_f32 v[120:121], v[124:125], v[120:121]
	v_lshlrev_b32_e32 v124, 16, v133
	v_mul_f32_e32 v73, 0xbfb8aa3b, v124
	v_exp_f32_e32 v73, v73
	v_and_b32_e32 v125, 0xffff0000, v133
	v_add_f32_e32 v73, 1.0, v73
	v_rcp_f32_e32 v132, v73
	v_mul_f32_e32 v73, 0xbfb8aa3b, v125
	v_exp_f32_e32 v73, v73
	s_nop 0
	v_add_f32_e32 v73, 1.0, v73
	v_rcp_f32_e32 v133, v73
	v_pk_fma_f32 v[122:123], v[34:35], v[72:73], v[122:123] op_sel_hi:[1,0,1] neg_lo:[0,0,1] neg_hi:[0,0,1]
	v_pk_mul_f32 v[34:35], v[144:145], v[126:127]
	v_pk_mul_f32 v[174:175], v[122:123], v[122:123]
	v_pk_mul_f32 v[124:125], v[132:133], v[124:125]
	v_pk_fma_f32 v[132:133], v[32:33], v[72:73], v[34:35] op_sel_hi:[1,0,1] neg_lo:[0,0,1] neg_hi:[0,0,1]
	v_lshlrev_b32_e32 v32, 16, v180
	v_and_b32_e32 v33, 0xffff0000, v180
	v_mul_f32_e32 v34, 0xbfb8aa3b, v32
	v_mul_f32_e32 v35, 0xbfb8aa3b, v33
	v_exp_f32_e32 v34, v34
	v_exp_f32_e32 v35, v35
	v_pk_mul_f32 v[176:177], v[132:133], v[132:133]
	v_add_f32_e32 v34, 1.0, v34
	v_add_f32_e32 v35, 1.0, v35
	v_rcp_f32_e32 v34, v34
	v_rcp_f32_e32 v35, v35
	s_nop 0
	v_pk_mul_f32 v[140:141], v[34:35], v[32:33]
	v_lshlrev_b32_e32 v32, 16, v181
	v_and_b32_e32 v33, 0xffff0000, v181
	v_mul_f32_e32 v34, 0xbfb8aa3b, v32
	v_mul_f32_e32 v35, 0xbfb8aa3b, v33
	v_exp_f32_e32 v34, v34
	v_exp_f32_e32 v35, v35
	v_add_f32_e32 v34, 1.0, v34
	v_add_f32_e32 v35, 1.0, v35
	v_rcp_f32_e32 v34, v34
	v_rcp_f32_e32 v35, v35
	s_nop 0
	v_pk_mul_f32 v[126:127], v[34:35], v[32:33]
	v_pk_mul_f32 v[34:35], v[144:145], v[128:129]
	v_pk_mul_f32 v[32:33], v[144:145], v[134:135]
	v_pk_fma_f32 v[128:129], v[36:37], v[72:73], v[34:35] op_sel_hi:[1,0,1] neg_lo:[0,0,1] neg_hi:[0,0,1]
	v_lshlrev_b32_e32 v34, 16, v186
	v_and_b32_e32 v35, 0xffff0000, v186
	v_mul_f32_e32 v36, 0xbfb8aa3b, v34
	v_mul_f32_e32 v37, 0xbfb8aa3b, v35
	v_exp_f32_e32 v36, v36
	v_exp_f32_e32 v37, v37
	v_pk_fma_f32 v[32:33], v[38:39], v[72:73], v[32:33] op_sel_hi:[1,0,1] neg_lo:[0,0,1] neg_hi:[0,0,1]
	v_pk_mul_f32 v[182:183], v[128:129], v[128:129]
	v_add_f32_e32 v36, 1.0, v36
	v_add_f32_e32 v37, 1.0, v37
	v_rcp_f32_e32 v36, v36
	v_rcp_f32_e32 v37, v37
	v_pk_mul_f32 v[180:181], v[32:33], v[32:33]
	v_pk_mul_f32 v[134:135], v[36:37], v[34:35]
	v_lshlrev_b32_e32 v34, 16, v187
	v_and_b32_e32 v35, 0xffff0000, v187
	v_mul_f32_e32 v36, 0xbfb8aa3b, v34
	v_mul_f32_e32 v37, 0xbfb8aa3b, v35
	v_exp_f32_e32 v36, v36
	v_exp_f32_e32 v37, v37
	v_add_f32_e32 v36, 1.0, v36
	v_add_f32_e32 v37, 1.0, v37
	v_rcp_f32_e32 v36, v36
	v_rcp_f32_e32 v37, v37
	s_nop 0
	v_pk_mul_f32 v[38:39], v[36:37], v[34:35]
	v_pk_mul_f32 v[36:37], v[144:145], v[130:131]
	v_pk_mul_f32 v[34:35], v[144:145], v[138:139]
	v_pk_fma_f32 v[130:131], v[40:41], v[72:73], v[36:37] op_sel_hi:[1,0,1] neg_lo:[0,0,1] neg_hi:[0,0,1]
	v_lshlrev_b32_e32 v36, 16, v184
	v_and_b32_e32 v37, 0xffff0000, v184
	v_mul_f32_e32 v40, 0xbfb8aa3b, v36
	v_mul_f32_e32 v41, 0xbfb8aa3b, v37
	v_exp_f32_e32 v40, v40
	v_exp_f32_e32 v41, v41
	v_pk_fma_f32 v[34:35], v[42:43], v[72:73], v[34:35] op_sel_hi:[1,0,1] neg_lo:[0,0,1] neg_hi:[0,0,1]
	v_pk_mul_f32 v[42:43], v[144:145], v[142:143]
	v_add_f32_e32 v40, 1.0, v40
	v_add_f32_e32 v41, 1.0, v41
	v_rcp_f32_e32 v40, v40
	v_rcp_f32_e32 v41, v41
	v_pk_mul_f32 v[188:189], v[130:131], v[130:131]
	v_pk_mul_f32 v[186:187], v[34:35], v[34:35]
	v_pk_mul_f32 v[138:139], v[40:41], v[36:37]
	v_lshlrev_b32_e32 v36, 16, v185
	v_and_b32_e32 v37, 0xffff0000, v185
	v_mul_f32_e32 v40, 0xbfb8aa3b, v36
	v_mul_f32_e32 v41, 0xbfb8aa3b, v37
	v_exp_f32_e32 v40, v40
	v_exp_f32_e32 v41, v41
	v_add_f32_e32 v40, 1.0, v40
	v_add_f32_e32 v41, 1.0, v41
	v_rcp_f32_e32 v40, v40
	v_rcp_f32_e32 v41, v41
	s_nop 0
	v_pk_mul_f32 v[40:41], v[40:41], v[36:37]
	v_pk_mul_f32 v[36:37], v[144:145], v[166:167]
	s_nop 0
	v_pk_fma_f32 v[36:37], v[46:47], v[72:73], v[36:37] op_sel_hi:[1,0,1] neg_lo:[0,0,1] neg_hi:[0,0,1]
	v_pk_fma_f32 v[46:47], v[44:45], v[72:73], v[42:43] op_sel_hi:[1,0,1] neg_lo:[0,0,1] neg_hi:[0,0,1]
	v_lshlrev_b32_e32 v42, 16, v178
	v_and_b32_e32 v43, 0xffff0000, v178
	v_mul_f32_e32 v44, 0xbfb8aa3b, v42
	v_mul_f32_e32 v45, 0xbfb8aa3b, v43
	v_exp_f32_e32 v44, v44
	v_exp_f32_e32 v45, v45
	v_pk_mul_f32 v[184:185], v[46:47], v[46:47]
	v_pk_mul_f32 v[166:167], v[36:37], v[36:37]
	v_add_f32_e32 v44, 1.0, v44
	v_add_f32_e32 v45, 1.0, v45
	v_rcp_f32_e32 v44, v44
	v_rcp_f32_e32 v45, v45
	s_nop 0
	v_pk_mul_f32 v[142:143], v[44:45], v[42:43]
	v_lshlrev_b32_e32 v42, 16, v179
	v_and_b32_e32 v43, 0xffff0000, v179
	v_mul_f32_e32 v44, 0xbfb8aa3b, v42
	v_mul_f32_e32 v45, 0xbfb8aa3b, v43
	v_exp_f32_e32 v44, v44
	v_exp_f32_e32 v45, v45
	v_add_f32_e32 v44, 1.0, v44
	v_add_f32_e32 v45, 1.0, v45
	v_rcp_f32_e32 v44, v44
	v_rcp_f32_e32 v45, v45
	s_nop 0
	v_pk_mul_f32 v[42:43], v[44:45], v[42:43]
	v_pk_mul_f32 v[44:45], v[144:145], v[148:149]
	s_nop 0
	v_pk_fma_f32 v[18:19], v[18:19], v[72:73], v[44:45] op_sel_hi:[1,0,1] neg_lo:[0,0,1] neg_hi:[0,0,1]
	v_pk_mul_f32 v[44:45], v[144:145], v[136:137]
	v_pk_mul_f32 v[178:179], v[18:19], v[18:19]
	v_pk_fma_f32 v[136:137], v[16:17], v[72:73], v[44:45] op_sel_hi:[1,0,1] neg_lo:[0,0,1] neg_hi:[0,0,1]
	v_lshlrev_b32_e32 v16, 16, v146
	v_and_b32_e32 v17, 0xffff0000, v146
	v_mul_f32_e32 v44, 0xbfb8aa3b, v16
	v_mul_f32_e32 v45, 0xbfb8aa3b, v17
	v_exp_f32_e32 v44, v44
	v_exp_f32_e32 v45, v45
	v_pk_mul_f32 v[190:191], v[136:137], v[136:137]
	v_add_f32_e32 v44, 1.0, v44
	v_add_f32_e32 v45, 1.0, v45
	v_rcp_f32_e32 v44, v44
	v_rcp_f32_e32 v45, v45
	s_nop 0
	v_pk_mul_f32 v[148:149], v[44:45], v[16:17]
	v_lshlrev_b32_e32 v16, 16, v147
	v_and_b32_e32 v17, 0xffff0000, v147
	v_mul_f32_e32 v44, 0xbfb8aa3b, v16
	v_mul_f32_e32 v45, 0xbfb8aa3b, v17
	v_exp_f32_e32 v44, v44
	v_exp_f32_e32 v45, v45
	v_add_f32_e32 v44, 1.0, v44
	v_add_f32_e32 v45, 1.0, v45
	v_rcp_f32_e32 v44, v44
	v_rcp_f32_e32 v45, v45
	s_nop 0
	v_pk_mul_f32 v[44:45], v[44:45], v[16:17]
	v_pk_mul_f32 v[16:17], v[144:145], v[152:153]
	s_nop 0
	v_pk_fma_f32 v[16:17], v[22:23], v[72:73], v[16:17] op_sel_hi:[1,0,1] neg_lo:[0,0,1] neg_hi:[0,0,1]
	v_pk_mul_f32 v[22:23], v[144:145], v[150:151]
	v_pk_mul_f32 v[152:153], v[16:17], v[16:17]
	v_pk_fma_f32 v[146:147], v[20:21], v[72:73], v[22:23] op_sel_hi:[1,0,1] neg_lo:[0,0,1] neg_hi:[0,0,1]
	v_lshlrev_b32_e32 v20, 16, v168
	v_and_b32_e32 v21, 0xffff0000, v168
	v_mul_f32_e32 v22, 0xbfb8aa3b, v20
	v_mul_f32_e32 v23, 0xbfb8aa3b, v21
	v_exp_f32_e32 v22, v22
	v_exp_f32_e32 v23, v23
	v_pk_mul_f32 v[194:195], v[146:147], v[146:147]
	v_add_f32_e32 v22, 1.0, v22
	v_add_f32_e32 v23, 1.0, v23
	v_rcp_f32_e32 v22, v22
	v_rcp_f32_e32 v23, v23
	s_nop 0
	v_pk_mul_f32 v[150:151], v[22:23], v[20:21]
	v_lshlrev_b32_e32 v20, 16, v169
	v_and_b32_e32 v21, 0xffff0000, v169
	v_mul_f32_e32 v22, 0xbfb8aa3b, v20
	v_mul_f32_e32 v23, 0xbfb8aa3b, v21
	v_exp_f32_e32 v22, v22
	v_exp_f32_e32 v23, v23
	v_add_f32_e32 v22, 1.0, v22
	v_add_f32_e32 v23, 1.0, v23
	v_rcp_f32_e32 v22, v22
	v_rcp_f32_e32 v23, v23
	s_nop 0
	v_pk_mul_f32 v[22:23], v[22:23], v[20:21]
	v_pk_mul_f32 v[20:21], v[144:145], v[106:107]
	s_nop 0
	v_pk_fma_f32 v[20:21], v[26:27], v[72:73], v[20:21] op_sel_hi:[1,0,1] neg_lo:[0,0,1] neg_hi:[0,0,1]
	v_pk_mul_f32 v[26:27], v[144:145], v[102:103]
	v_pk_mul_f32 v[168:169], v[20:21], v[20:21]
	v_pk_fma_f32 v[102:103], v[24:25], v[72:73], v[26:27] op_sel_hi:[1,0,1] neg_lo:[0,0,1] neg_hi:[0,0,1]
	v_lshlrev_b32_e32 v24, 16, v160
	v_and_b32_e32 v25, 0xffff0000, v160
	v_mul_f32_e32 v26, 0xbfb8aa3b, v24
	v_mul_f32_e32 v27, 0xbfb8aa3b, v25
	v_exp_f32_e32 v26, v26
	v_exp_f32_e32 v27, v27
	v_pk_mul_f32 v[196:197], v[102:103], v[102:103]
	v_add_f32_e32 v26, 1.0, v26
	v_add_f32_e32 v27, 1.0, v27
	v_rcp_f32_e32 v26, v26
	v_rcp_f32_e32 v27, v27
	s_nop 0
	v_pk_mul_f32 v[106:107], v[26:27], v[24:25]
	v_lshlrev_b32_e32 v24, 16, v161
	v_and_b32_e32 v25, 0xffff0000, v161
	v_mul_f32_e32 v26, 0xbfb8aa3b, v24
	v_mul_f32_e32 v27, 0xbfb8aa3b, v25
	v_exp_f32_e32 v26, v26
	v_exp_f32_e32 v27, v27
	v_add_f32_e32 v26, 1.0, v26
	v_add_f32_e32 v27, 1.0, v27
	v_rcp_f32_e32 v26, v26
	v_rcp_f32_e32 v27, v27
	s_nop 0
	v_pk_mul_f32 v[26:27], v[26:27], v[24:25]
	v_pk_mul_f32 v[24:25], v[144:145], v[92:93]
	s_nop 0
	v_pk_fma_f32 v[24:25], v[30:31], v[72:73], v[24:25] op_sel_hi:[1,0,1] neg_lo:[0,0,1] neg_hi:[0,0,1]
	v_pk_mul_f32 v[30:31], v[144:145], v[90:91]
	v_pk_mul_f32 v[160:161], v[24:25], v[24:25]
	v_pk_fma_f32 v[90:91], v[28:29], v[72:73], v[30:31] op_sel_hi:[1,0,1] neg_lo:[0,0,1] neg_hi:[0,0,1]
	v_lshlrev_b32_e32 v28, 16, v154
	v_and_b32_e32 v29, 0xffff0000, v154
	v_mul_f32_e32 v30, 0xbfb8aa3b, v28
	v_mul_f32_e32 v31, 0xbfb8aa3b, v29
	v_exp_f32_e32 v30, v30
	v_exp_f32_e32 v31, v31
	v_pk_mul_f32 v[198:199], v[90:91], v[90:91]
	v_add_f32_e32 v30, 1.0, v30
	v_add_f32_e32 v31, 1.0, v31
	v_rcp_f32_e32 v30, v30
	v_rcp_f32_e32 v31, v31
	s_nop 0
	v_pk_mul_f32 v[92:93], v[30:31], v[28:29]
	v_lshlrev_b32_e32 v28, 16, v155
	v_and_b32_e32 v29, 0xffff0000, v155
	v_mul_f32_e32 v30, 0xbfb8aa3b, v28
	v_mul_f32_e32 v31, 0xbfb8aa3b, v29
	v_exp_f32_e32 v30, v30
	v_exp_f32_e32 v31, v31
	v_add_f32_e32 v30, 1.0, v30
	v_add_f32_e32 v31, 1.0, v31
	v_rcp_f32_e32 v30, v30
	v_rcp_f32_e32 v31, v31
	s_nop 0
	v_pk_mul_f32 v[28:29], v[30:31], v[28:29]
	v_pk_mul_f32 v[30:31], v[144:145], v[88:89]
	s_nop 0
	v_pk_fma_f32 v[2:3], v[2:3], v[72:73], v[30:31] op_sel_hi:[1,0,1] neg_lo:[0,0,1] neg_hi:[0,0,1]
	v_pk_mul_f32 v[30:31], v[144:145], v[86:87]
	v_pk_mul_f32 v[154:155], v[2:3], v[2:3]
	v_pk_fma_f32 v[86:87], v[0:1], v[72:73], v[30:31] op_sel_hi:[1,0,1] neg_lo:[0,0,1] neg_hi:[0,0,1]
	v_lshlrev_b32_e32 v0, 16, v118
	v_and_b32_e32 v1, 0xffff0000, v118
	v_mul_f32_e32 v30, 0xbfb8aa3b, v0
	v_mul_f32_e32 v31, 0xbfb8aa3b, v1
	v_exp_f32_e32 v30, v30
	v_exp_f32_e32 v31, v31
	v_pk_mul_f32 v[200:201], v[86:87], v[86:87]
	v_add_f32_e32 v30, 1.0, v30
	v_add_f32_e32 v31, 1.0, v31
	v_rcp_f32_e32 v30, v30
	v_rcp_f32_e32 v31, v31
	s_nop 0
	v_pk_mul_f32 v[88:89], v[30:31], v[0:1]
	v_lshlrev_b32_e32 v0, 16, v119
	v_and_b32_e32 v1, 0xffff0000, v119
	v_mul_f32_e32 v30, 0xbfb8aa3b, v0
	v_mul_f32_e32 v31, 0xbfb8aa3b, v1
	v_exp_f32_e32 v30, v30
	v_exp_f32_e32 v31, v31
	v_add_f32_e32 v30, 1.0, v30
	v_add_f32_e32 v31, 1.0, v31
	v_rcp_f32_e32 v30, v30
	v_rcp_f32_e32 v31, v31
	s_nop 0
	v_pk_mul_f32 v[30:31], v[30:31], v[0:1]
	v_pk_mul_f32 v[0:1], v[144:145], v[84:85]
	s_nop 0
	v_pk_fma_f32 v[0:1], v[6:7], v[72:73], v[0:1] op_sel_hi:[1,0,1] neg_lo:[0,0,1] neg_hi:[0,0,1]
	v_pk_mul_f32 v[6:7], v[144:145], v[82:83]
	v_pk_mul_f32 v[84:85], v[0:1], v[0:1]
	v_pk_fma_f32 v[6:7], v[4:5], v[72:73], v[6:7] op_sel_hi:[1,0,1] neg_lo:[0,0,1] neg_hi:[0,0,1]
	v_lshlrev_b32_e32 v4, 16, v94
	v_mul_f32_e32 v73, 0xbfb8aa3b, v4
	v_exp_f32_e32 v73, v73
	v_and_b32_e32 v5, 0xffff0000, v94
	v_pk_mul_f32 v[118:119], v[6:7], v[6:7]
	v_add_f32_e32 v73, 1.0, v73
	v_rcp_f32_e32 v82, v73
	v_mul_f32_e32 v73, 0xbfb8aa3b, v5
	v_exp_f32_e32 v73, v73
	s_nop 0
	v_add_f32_e32 v73, 1.0, v73
	v_rcp_f32_e32 v83, v73
	s_nop 0
	v_pk_mul_f32 v[82:83], v[82:83], v[4:5]
	v_lshlrev_b32_e32 v4, 16, v95
	v_mul_f32_e32 v73, 0xbfb8aa3b, v4
	v_exp_f32_e32 v73, v73
	v_and_b32_e32 v5, 0xffff0000, v95
	v_add_f32_e32 v73, 1.0, v73
	v_rcp_f32_e32 v94, v73
	v_mul_f32_e32 v73, 0xbfb8aa3b, v5
	v_exp_f32_e32 v73, v73
	s_nop 0
	v_add_f32_e32 v73, 1.0, v73
	v_rcp_f32_e32 v95, v73
	v_pk_fma_f32 v[10:11], v[10:11], v[72:73], v[80:81] op_sel_hi:[1,0,1] neg_lo:[0,0,1] neg_hi:[0,0,1]
	v_pk_fma_f32 v[72:73], v[8:9], v[72:73], v[78:79] op_sel_hi:[1,0,1] neg_lo:[0,0,1] neg_hi:[0,0,1]
	v_lshlrev_b32_e32 v78, 16, v70
	v_and_b32_e32 v79, 0xffff0000, v70
	v_mul_f32_e32 v70, 0xbfb8aa3b, v78
	v_exp_f32_e32 v70, v70
	v_pk_mul_f32 v[4:5], v[94:95], v[4:5]
	v_pk_mul_f32 v[8:9], v[72:73], v[72:73]
	v_pk_mul_f32 v[80:81], v[10:11], v[10:11]
	v_add_f32_e32 v70, 1.0, v70
	v_rcp_f32_e32 v94, v70
	v_mul_f32_e32 v70, 0xbfb8aa3b, v79
	v_exp_f32_e32 v70, v70
	s_nop 0
	v_add_f32_e32 v70, 1.0, v70
	v_rcp_f32_e32 v95, v70
	v_add_f32_e32 v70, v116, v117
	v_add_f32_e32 v70, v70, v110
	v_add_f32_e32 v70, v70, v111
	v_add_f32_e32 v70, v70, v158
	v_add_f32_e32 v70, v70, v159
	v_add_f32_e32 v70, v70, v156
	v_add_f32_e32 v70, v70, v157
	v_add_f32_e32 v70, v70, v164
	v_add_f32_e32 v70, v70, v165
	v_add_f32_e32 v70, v70, v162
	v_add_f32_e32 v70, v70, v163
	v_add_f32_e32 v70, v70, v172
	v_add_f32_e32 v70, v70, v173
	v_add_f32_e32 v70, v70, v170
	v_add_f32_e32 v70, v70, v171
	v_add_f32_e32 v70, v70, v176
	v_add_f32_e32 v70, v70, v177
	v_add_f32_e32 v70, v70, v174
	v_add_f32_e32 v70, v70, v175
	v_add_f32_e32 v70, v70, v182
	v_add_f32_e32 v70, v70, v183
	v_add_f32_e32 v70, v70, v180
	v_add_f32_e32 v70, v70, v181
	v_add_f32_e32 v70, v70, v188
	v_add_f32_e32 v70, v70, v189
	v_add_f32_e32 v70, v70, v186
	v_add_f32_e32 v70, v70, v187
	v_add_f32_e32 v70, v70, v184
	v_add_f32_e32 v70, v70, v185
	v_add_f32_e32 v70, v70, v166
	v_add_f32_e32 v70, v70, v167
	v_add_f32_e32 v70, v70, v190
	v_add_f32_e32 v70, v70, v191
	v_add_f32_e32 v70, v70, v178
	v_add_f32_e32 v70, v70, v179
	v_add_f32_e32 v70, v70, v194
	v_add_f32_e32 v70, v70, v195
	v_add_f32_e32 v70, v70, v152
	v_add_f32_e32 v70, v70, v153
	v_add_f32_e32 v70, v70, v196
	v_add_f32_e32 v70, v70, v197
	v_add_f32_e32 v70, v70, v168
	v_add_f32_e32 v70, v70, v169
	v_add_f32_e32 v70, v70, v198
	v_add_f32_e32 v70, v70, v199
	v_add_f32_e32 v70, v70, v160
	v_add_f32_e32 v70, v70, v161
	v_add_f32_e32 v70, v70, v200
	v_add_f32_e32 v70, v70, v201
	v_add_f32_e32 v70, v70, v154
	v_add_f32_e32 v70, v70, v155
	v_add_f32_e32 v70, v70, v118
	v_add_f32_e32 v70, v70, v119
	v_add_f32_e32 v70, v70, v84
	v_add_f32_e32 v70, v70, v85
	v_add_f32_e32 v8, v70, v8
	v_add_f32_e32 v8, v8, v9
	v_add_f32_e32 v8, v8, v80
	v_add_f32_e32 v8, v8, v81
	v_add_f32_e32 v8, v8, v74
	v_add_f32_e32 v8, v8, v75
	v_add_f32_e32 v8, v8, v76
	v_add_f32_e32 v8, v8, v77
	ds_bpermute_b32 v9, v218, v8
	v_pk_mul_f32 v[78:79], v[94:95], v[78:79]
	s_waitcnt lgkmcnt(0)
	v_add_f32_e32 v8, v8, v9
	v_fmamk_f32 v8, v8, 0x3c000000, v207
	v_cmp_gt_f32_e32 vcc, s2, v8
	v_mul_f32_e32 v9, 0x4b800000, v8
	s_nop 0
	v_cndmask_b32_e32 v8, v8, v9, vcc
	v_rsq_f32_e32 v8, v8
	s_nop 0
	v_mul_f32_e32 v9, 0x45800000, v8
	v_cndmask_b32_e32 v8, v8, v9, vcc
	v_mul_f32_e32 v8, v204, v8
	v_pk_mul_f32 v[74:75], v[96:97], v[8:9] op_sel_hi:[1,0]
	v_pk_mul_f32 v[50:51], v[50:51], v[8:9] op_sel_hi:[1,0]
	v_pk_mul_f32 v[12:13], v[74:75], v[12:13]
	v_pk_mul_f32 v[14:15], v[50:51], v[14:15]
	v_pk_mul_f32 v[12:13], v[98:99], v[12:13]
	v_pk_mul_f32 v[14:15], v[100:101], v[14:15]
	v_cvt_pk_bf16_f32 v12, v12, v13
	v_cvt_pk_bf16_f32 v13, v14, v15
	flat_store_dwordx2 v[48:49], v[12:13] offset:1024
	global_load_dwordx4 v[252:255], v205, s[0:1] offset:128
	v_pk_mul_f32 v[50:51], v[52:53], v[8:9] op_sel_hi:[1,0]
	v_pk_mul_f32 v[32:33], v[32:33], v[8:9] op_sel_hi:[1,0]
	v_pk_mul_f32 v[18:19], v[18:19], v[8:9] op_sel_hi:[1,0]
	v_pk_mul_f32 v[16:17], v[16:17], v[8:9] op_sel_hi:[1,0]
	v_pk_mul_f32 v[2:3], v[2:3], v[8:9] op_sel_hi:[1,0]
	v_pk_mul_f32 v[0:1], v[0:1], v[8:9] op_sel_hi:[1,0]
	v_pk_mul_f32 v[10:11], v[10:11], v[8:9] op_sel_hi:[1,0]
	v_pk_mul_f32 v[12:13], v[50:51], v[240:241]
	v_pk_mul_f32 v[50:51], v[54:55], v[8:9] op_sel_hi:[1,0]
	v_pk_mul_f32 v[12:13], v[104:105], v[12:13]
	v_pk_mul_f32 v[14:15], v[50:51], v[242:243]
	v_cvt_pk_bf16_f32 v12, v12, v13
	v_pk_mul_f32 v[14:15], v[108:109], v[14:15]
	v_pk_mul_f32 v[50:51], v[56:57], v[8:9] op_sel_hi:[1,0]
	v_cvt_pk_bf16_f32 v13, v14, v15
	flat_store_dwordx2 v[48:49], v[12:13] offset:1040
	global_load_dwordx4 v[240:243], v205, s[0:1] offset:160
	v_pk_mul_f32 v[12:13], v[50:51], v[244:245]
	v_pk_mul_f32 v[50:51], v[58:59], v[8:9] op_sel_hi:[1,0]
	v_pk_mul_f32 v[12:13], v[112:113], v[12:13]
	v_pk_mul_f32 v[14:15], v[50:51], v[246:247]
	v_cvt_pk_bf16_f32 v12, v12, v13
	v_pk_mul_f32 v[14:15], v[114:115], v[14:15]
	v_pk_mul_f32 v[50:51], v[60:61], v[8:9] op_sel_hi:[1,0]
	v_cvt_pk_bf16_f32 v13, v14, v15
	flat_store_dwordx2 v[48:49], v[12:13] offset:1056
	global_load_dwordx4 v[244:247], v205, s[0:1] offset:192
	v_pk_mul_f32 v[12:13], v[50:51], v[248:249]
	v_pk_mul_f32 v[50:51], v[62:63], v[8:9] op_sel_hi:[1,0]
	v_pk_mul_f32 v[12:13], v[120:121], v[12:13]
	v_pk_mul_f32 v[14:15], v[50:51], v[250:251]
	v_cvt_pk_bf16_f32 v12, v12, v13
	v_pk_mul_f32 v[14:15], v[124:125], v[14:15]
	v_pk_mul_f32 v[50:51], v[132:133], v[8:9] op_sel_hi:[1,0]
	v_cvt_pk_bf16_f32 v13, v14, v15
	flat_store_dwordx2 v[48:49], v[12:13] offset:1072
	global_load_dwordx4 v[248:251], v205, s[0:1] offset:224
	s_waitcnt vmcnt(6)
	v_pk_mul_f32 v[12:13], v[50:51], v[252:253]
	v_pk_mul_f32 v[50:51], v[122:123], v[8:9] op_sel_hi:[1,0]
	v_pk_mul_f32 v[12:13], v[140:141], v[12:13]
	v_pk_mul_f32 v[14:15], v[50:51], v[254:255]
	v_cvt_pk_bf16_f32 v12, v12, v13
	v_pk_mul_f32 v[14:15], v[126:127], v[14:15]
	v_pk_mul_f32 v[50:51], v[128:129], v[8:9] op_sel_hi:[1,0]
	v_cvt_pk_bf16_f32 v13, v14, v15
	flat_store_dwordx2 v[48:49], v[12:13] offset:1088
	global_load_dwordx4 v[252:255], v205, s[0:1] offset:256
	s_waitcnt vmcnt(6)
	v_pk_mul_f32 v[12:13], v[50:51], v[240:241]
	v_pk_mul_f32 v[14:15], v[32:33], v[242:243]
	v_pk_mul_f32 v[12:13], v[134:135], v[12:13]
	v_pk_mul_f32 v[14:15], v[38:39], v[14:15]
	v_cvt_pk_bf16_f32 v12, v12, v13
	v_cvt_pk_bf16_f32 v13, v14, v15
	flat_store_dwordx2 v[48:49], v[12:13] offset:1104
	global_load_dwordx4 v[240:243], v205, s[0:1] offset:288
	v_pk_mul_f32 v[32:33], v[130:131], v[8:9] op_sel_hi:[1,0]
	s_waitcnt vmcnt(6)
	v_pk_mul_f32 v[12:13], v[32:33], v[244:245]
	v_pk_mul_f32 v[32:33], v[34:35], v[8:9] op_sel_hi:[1,0]
	v_pk_mul_f32 v[12:13], v[138:139], v[12:13]
	v_pk_mul_f32 v[14:15], v[32:33], v[246:247]
	v_cvt_pk_bf16_f32 v12, v12, v13
	v_pk_mul_f32 v[14:15], v[40:41], v[14:15]
	v_pk_mul_f32 v[32:33], v[46:47], v[8:9] op_sel_hi:[1,0]
	v_cvt_pk_bf16_f32 v13, v14, v15
	flat_store_dwordx2 v[48:49], v[12:13] offset:1120
	global_load_dwordx4 v[244:247], v205, s[0:1] offset:320
	s_waitcnt vmcnt(6)
	v_pk_mul_f32 v[12:13], v[32:33], v[248:249]
	v_pk_mul_f32 v[32:33], v[36:37], v[8:9] op_sel_hi:[1,0]
	v_pk_mul_f32 v[12:13], v[142:143], v[12:13]
	v_pk_mul_f32 v[14:15], v[32:33], v[250:251]
	v_cvt_pk_bf16_f32 v12, v12, v13
	v_pk_mul_f32 v[14:15], v[42:43], v[14:15]
	v_pk_mul_f32 v[32:33], v[136:137], v[8:9] op_sel_hi:[1,0]
	v_cvt_pk_bf16_f32 v13, v14, v15
	flat_store_dwordx2 v[48:49], v[12:13] offset:1136
	global_load_dwordx4 v[248:251], v205, s[0:1] offset:352
	s_waitcnt vmcnt(6)
	v_pk_mul_f32 v[12:13], v[32:33], v[252:253]
	v_pk_mul_f32 v[14:15], v[18:19], v[254:255]
	v_pk_mul_f32 v[12:13], v[148:149], v[12:13]
	v_pk_mul_f32 v[14:15], v[44:45], v[14:15]
	v_cvt_pk_bf16_f32 v12, v12, v13
	v_cvt_pk_bf16_f32 v13, v14, v15
	flat_store_dwordx2 v[48:49], v[12:13] offset:1152
	global_load_dwordx4 v[252:255], v205, s[0:1] offset:384
	v_pk_mul_f32 v[18:19], v[146:147], v[8:9] op_sel_hi:[1,0]
	s_waitcnt vmcnt(6)
	v_pk_mul_f32 v[14:15], v[16:17], v[242:243]
	v_pk_mul_f32 v[12:13], v[18:19], v[240:241]
	v_pk_mul_f32 v[14:15], v[22:23], v[14:15]
	v_pk_mul_f32 v[12:13], v[150:151], v[12:13]
	v_pk_mul_f32 v[16:17], v[102:103], v[8:9] op_sel_hi:[1,0]
	v_cvt_pk_bf16_f32 v12, v12, v13
	v_cvt_pk_bf16_f32 v13, v14, v15
	flat_store_dwordx2 v[48:49], v[12:13] offset:1168
	global_load_dwordx4 v[240:243], v205, s[0:1] offset:416
	s_waitcnt vmcnt(6)
	v_pk_mul_f32 v[12:13], v[16:17], v[244:245]
	v_pk_mul_f32 v[16:17], v[20:21], v[8:9] op_sel_hi:[1,0]
	v_pk_mul_f32 v[12:13], v[106:107], v[12:13]
	v_pk_mul_f32 v[14:15], v[16:17], v[246:247]
	v_cvt_pk_bf16_f32 v12, v12, v13
	v_pk_mul_f32 v[14:15], v[26:27], v[14:15]
	v_pk_mul_f32 v[16:17], v[90:91], v[8:9] op_sel_hi:[1,0]
	v_cvt_pk_bf16_f32 v13, v14, v15
	flat_store_dwordx2 v[48:49], v[12:13] offset:1184
	global_load_dwordx4 v[244:247], v205, s[0:1] offset:448
	s_waitcnt vmcnt(6)
	v_pk_mul_f32 v[12:13], v[16:17], v[248:249]
	v_pk_mul_f32 v[16:17], v[24:25], v[8:9] op_sel_hi:[1,0]
	v_pk_mul_f32 v[12:13], v[92:93], v[12:13]
	v_pk_mul_f32 v[14:15], v[16:17], v[250:251]
	v_cvt_pk_bf16_f32 v12, v12, v13
	v_pk_mul_f32 v[14:15], v[28:29], v[14:15]
	v_pk_mul_f32 v[16:17], v[86:87], v[8:9] op_sel_hi:[1,0]
	v_cvt_pk_bf16_f32 v13, v14, v15
	flat_store_dwordx2 v[48:49], v[12:13] offset:1200
	global_load_dwordx4 v[248:251], v205, s[0:1] offset:480
	s_waitcnt vmcnt(6)
	v_pk_mul_f32 v[12:13], v[16:17], v[252:253]
	v_pk_mul_f32 v[2:3], v[2:3], v[254:255]
	v_pk_mul_f32 v[12:13], v[88:89], v[12:13]
	v_pk_mul_f32 v[2:3], v[30:31], v[2:3]
	v_cvt_pk_bf16_f32 v12, v12, v13
	v_cvt_pk_bf16_f32 v13, v2, v3
	flat_store_dwordx2 v[48:49], v[12:13] offset:1216
	v_pk_mul_f32 v[2:3], v[6:7], v[8:9] op_sel_hi:[1,0]
	s_waitcnt vmcnt(5)
	v_pk_mul_f32 v[0:1], v[0:1], v[242:243]
	v_pk_mul_f32 v[2:3], v[2:3], v[240:241]
	v_pk_mul_f32 v[0:1], v[4:5], v[0:1]
	v_pk_mul_f32 v[2:3], v[82:83], v[2:3]
	v_pk_mul_f32 v[4:5], v[72:73], v[8:9] op_sel_hi:[1,0]
	v_cvt_pk_bf16_f32 v2, v2, v3
	v_cvt_pk_bf16_f32 v3, v0, v1
	flat_store_dwordx2 v[48:49], v[2:3] offset:1232
	s_waitcnt vmcnt(4)
	v_pk_mul_f32 v[0:1], v[4:5], v[244:245]
	s_nop 0
	v_pk_mul_f32 v[0:1], v[78:79], v[0:1]
	v_lshlrev_b32_e32 v4, 16, v71
	v_cvt_pk_bf16_f32 v0, v0, v1
	v_mul_f32_e32 v1, 0xbfb8aa3b, v4
	v_exp_f32_e32 v1, v1
	v_and_b32_e32 v5, 0xffff0000, v71
	v_pk_mul_f32 v[2:3], v[10:11], v[246:247]
	v_pk_mul_f32 v[10:11], v[66:67], v[8:9] op_sel_hi:[1,0]
	v_add_f32_e32 v1, 1.0, v1
	v_rcp_f32_e32 v6, v1
	v_mul_f32_e32 v1, 0xbfb8aa3b, v5
	v_exp_f32_e32 v1, v1
	v_pk_mul_f32 v[8:9], v[64:65], v[8:9] op_sel_hi:[1,0]
	v_add_f32_e32 v1, 1.0, v1
	v_rcp_f32_e32 v7, v1
	s_nop 0
	v_pk_mul_f32 v[4:5], v[6:7], v[4:5]
	s_nop 0
	v_pk_mul_f32 v[2:3], v[4:5], v[2:3]
	v_lshlrev_b32_e32 v4, 16, v68
	v_cvt_pk_bf16_f32 v1, v2, v3
	flat_store_dwordx2 v[48:49], v[0:1] offset:1248
	v_and_b32_e32 v5, 0xffff0000, v68
	v_mul_f32_e32 v6, 0xbfb8aa3b, v4
	v_mul_f32_e32 v7, 0xbfb8aa3b, v5
	v_exp_f32_e32 v6, v6
	v_exp_f32_e32 v7, v7
	v_add_f32_e32 v6, 1.0, v6
	v_add_f32_e32 v7, 1.0, v7
	v_rcp_f32_e32 v6, v6
	v_rcp_f32_e32 v7, v7
	s_waitcnt vmcnt(3)
	v_pk_mul_f32 v[0:1], v[10:11], v[248:249]
	v_pk_mul_f32 v[4:5], v[6:7], v[4:5]
	v_pk_mul_f32 v[2:3], v[8:9], v[250:251]
	v_pk_mul_f32 v[0:1], v[4:5], v[0:1]
	v_lshlrev_b32_e32 v4, 16, v69
	v_cvt_pk_bf16_f32 v0, v0, v1
	v_mul_f32_e32 v1, 0xbfb8aa3b, v4
	v_exp_f32_e32 v1, v1
	v_and_b32_e32 v5, 0xffff0000, v69
	v_add_f32_e32 v1, 1.0, v1
	v_rcp_f32_e32 v6, v1
	v_mul_f32_e32 v1, 0xbfb8aa3b, v5
	v_exp_f32_e32 v1, v1
	s_nop 0
	v_add_f32_e32 v1, 1.0, v1
	v_rcp_f32_e32 v7, v1
	s_nop 0
	v_pk_mul_f32 v[4:5], v[6:7], v[4:5]
	s_nop 0
	v_pk_mul_f32 v[2:3], v[4:5], v[2:3]
	s_nop 0
	v_cvt_pk_bf16_f32 v1, v2, v3
	flat_store_dwordx2 v[48:49], v[0:1] offset:1264
	s_branch .LBB0_829

.LBB0_956:
	s_cmpk_gt_u32 s37, 0xff
	s_waitcnt lgkmcnt(0)
	s_barrier
	s_cbranch_scc1 .LBB0_924
	s_lshl_b32 s0, s37, 8
	v_lshl_add_u32 v68, v64, 2, 0
	s_and_b32 s1, s0, 0xc000
	v_add_u32_e32 v69, s1, v68
	ds_read2st64_b32 v[96:97], v69 offset1:1
	ds_read2st64_b32 v[98:99], v69 offset0:2 offset1:3
	ds_read2st64_b32 v[112:113], v69 offset0:4 offset1:5
	ds_read2st64_b32 v[116:117], v69 offset0:6 offset1:7
	ds_read2st64_b32 v[118:119], v69 offset0:8 offset1:9
	ds_read2st64_b32 v[120:121], v69 offset0:10 offset1:11
	ds_read2st64_b32 v[122:123], v69 offset0:12 offset1:13
	ds_read2st64_b32 v[126:127], v69 offset0:14 offset1:15
	ds_read2st64_b32 v[128:129], v69 offset0:16 offset1:17
	ds_read2st64_b32 v[124:125], v69 offset0:18 offset1:19
	ds_read2st64_b32 v[130:131], v69 offset0:20 offset1:21
	ds_read2st64_b32 v[138:139], v69 offset0:22 offset1:23
	ds_read2st64_b32 v[132:133], v69 offset0:24 offset1:25
	ds_read2st64_b32 v[144:145], v69 offset0:26 offset1:27
	ds_read2st64_b32 v[148:149], v69 offset0:28 offset1:29
	ds_read2st64_b32 v[164:165], v69 offset0:30 offset1:31
	ds_read2st64_b32 v[140:141], v69 offset0:32 offset1:33
	ds_read2st64_b32 v[150:151], v69 offset0:34 offset1:35
	ds_read2st64_b32 v[134:135], v69 offset0:36 offset1:37
	ds_read2st64_b32 v[142:143], v69 offset0:38 offset1:39
	ds_read2st64_b32 v[104:105], v69 offset0:40 offset1:41
	ds_read2st64_b32 v[106:107], v69 offset0:42 offset1:43
	ds_read2st64_b32 v[90:91], v69 offset0:44 offset1:45
	ds_read2st64_b32 v[92:93], v69 offset0:46 offset1:47
	ds_read2st64_b32 v[86:87], v69 offset0:48 offset1:49
	ds_read2st64_b32 v[88:89], v69 offset0:50 offset1:51
	ds_read2st64_b32 v[82:83], v69 offset0:52 offset1:53
	ds_read2st64_b32 v[84:85], v69 offset0:54 offset1:55
	ds_read2st64_b32 v[78:79], v69 offset0:56 offset1:57
	ds_read2st64_b32 v[80:81], v69 offset0:58 offset1:59
	ds_read2st64_b32 v[64:65], v69 offset0:60 offset1:61
	s_or_b32 s0, s0, 0x3f00
	s_movk_i32 s6, 0x1400
	s_mov_b32 s3, s41
	s_waitcnt lgkmcnt(14)
	v_pk_mul_f32 v[96:97], v[160:161], v[96:97]
	s_waitcnt lgkmcnt(0)
	v_pk_mul_f32 v[64:65], v[160:161], v[64:65]
	v_pk_mul_f32 v[98:99], v[160:161], v[98:99]
	v_pk_fma_f32 v[66:67], v[12:13], v[72:73], v[64:65] op_sel_hi:[1,0,1] neg_lo:[0,0,1] neg_hi:[0,0,1]
	v_add_u32_e32 v13, s0, v68
	ds_read_b32 v12, v69 offset:15872
	ds_read_b32 v13, v13
	v_pk_mul_f32 v[112:113], v[160:161], v[112:113]
	v_pk_mul_f32 v[116:117], v[160:161], v[116:117]
	v_pk_mul_f32 v[118:119], v[160:161], v[118:119]
	v_pk_mul_f32 v[120:121], v[160:161], v[120:121]
	s_waitcnt lgkmcnt(0)
	v_pk_mul_f32 v[12:13], v[160:161], v[12:13]
	v_pk_mul_f32 v[122:123], v[160:161], v[122:123]
	v_pk_fma_f32 v[64:65], v[14:15], v[72:73], v[12:13] op_sel_hi:[1,0,1] neg_lo:[0,0,1] neg_hi:[0,0,1]
	v_mov_b64_e32 v[14:15], s[4:5]
	v_mad_u64_u32 v[14:15], s[0:1], v196, s6, v[14:15]
	v_mov_b32_e32 v68, v15
	v_mad_u64_u32 v[68:69], s[0:1], v195, s6, v[68:69]
	v_mov_b32_e32 v15, v68
	v_lshrrev_b32_e32 v68, 3, v194
	v_and_b32_e32 v73, 4, v68
	v_lshl_add_u64 v[12:13], v[162:163], 0, s[2:3]
	v_lshlrev_b32_e32 v192, 1, v73
	v_lshl_add_u64 v[12:13], v[12:13], 0, v[192:193]
	s_mov_b64 s[0:1], 0x1000
	v_lshl_add_u64 v[68:69], v[12:13], 0, s[0:1]
	s_movk_i32 s0, 0x1000
	v_add_co_u32_e32 v12, vcc, s0, v12
	v_pk_fma_f32 v[96:97], v[48:49], v[72:73], v[96:97] op_sel_hi:[1,0,1] neg_lo:[0,0,1] neg_hi:[0,0,1]
	s_nop 0
	v_addc_co_u32_e32 v13, vcc, 0, v13, vcc
	global_load_dwordx2 v[100:101], v[12:13], off
	global_load_dwordx2 v[162:163], v[68:69], off offset:16
	global_load_dwordx2 v[146:147], v[68:69], off offset:32
	global_load_dwordx2 v[136:137], v[68:69], off offset:48
	global_load_dwordx2 v[182:183], v[68:69], off offset:64
	global_load_dwordx2 v[188:189], v[68:69], off offset:80
	global_load_dwordx2 v[186:187], v[68:69], off offset:96
	global_load_dwordx2 v[180:181], v[68:69], off offset:112
	global_load_dwordx2 v[174:175], v[68:69], off offset:128
	global_load_dwordx2 v[168:169], v[68:69], off offset:144
	global_load_dwordx2 v[158:159], v[68:69], off offset:160
	global_load_dwordx2 v[152:153], v[68:69], off offset:176
	global_load_dwordx2 v[114:115], v[68:69], off offset:192
	global_load_dwordx2 v[94:95], v[68:69], off offset:208
	global_load_dwordx2 v[70:71], v[68:69], off offset:224
	s_nop 0
	global_load_dwordx2 v[68:69], v[68:69], off offset:240
	v_lshlrev_b32_e32 v205, 2, v73
	v_pk_fma_f32 v[50:51], v[50:51], v[72:73], v[98:99] op_sel_hi:[1,0,1] neg_lo:[0,0,1] neg_hi:[0,0,1]
	v_pk_mul_f32 v[126:127], v[160:161], v[126:127]
	v_pk_mul_f32 v[124:125], v[160:161], v[124:125]
	v_pk_mul_f32 v[80:81], v[160:161], v[80:81]
	v_pk_mul_f32 v[78:79], v[160:161], v[78:79]
	v_pk_mul_f32 v[110:111], v[96:97], v[96:97]
	v_lshl_add_u64 v[154:155], v[14:15], 0, s[2:3]
	global_load_dwordx4 v[12:15], v205, s[10:11]
	global_load_dwordx4 v[240:243], v205, s[10:11] offset:32
	global_load_dwordx4 v[244:247], v205, s[10:11] offset:64
	global_load_dwordx4 v[248:251], v205, s[10:11] offset:96
	v_pk_mul_f32 v[108:109], v[50:51], v[50:51]
	v_pk_mul_f32 v[74:75], v[66:67], v[66:67]
	v_pk_mul_f32 v[76:77], v[64:65], v[64:65]
	s_mov_b64 s[0:1], 0x24000400
	s_waitcnt vmcnt(0) lgkmcnt(0)
	v_lshlrev_b32_e32 v48, 16, v100
	v_mul_f32_e32 v73, 0xbfb8aa3b, v48
	v_exp_f32_e32 v73, v73
	v_and_b32_e32 v49, 0xffff0000, v100
	v_add_f32_e32 v73, 1.0, v73
	v_rcp_f32_e32 v98, v73
	v_mul_f32_e32 v73, 0xbfb8aa3b, v49
	v_exp_f32_e32 v73, v73
	s_nop 0
	v_add_f32_e32 v73, 1.0, v73
	v_rcp_f32_e32 v99, v73
	s_nop 0
	v_pk_mul_f32 v[98:99], v[98:99], v[48:49]
	v_lshlrev_b32_e32 v48, 16, v101
	v_mul_f32_e32 v73, 0xbfb8aa3b, v48
	v_exp_f32_e32 v73, v73
	v_and_b32_e32 v49, 0xffff0000, v101
	v_add_f32_e32 v73, 1.0, v73
	v_rcp_f32_e32 v100, v73
	v_mul_f32_e32 v73, 0xbfb8aa3b, v49
	v_exp_f32_e32 v73, v73
	s_nop 0
	v_add_f32_e32 v73, 1.0, v73
	v_pk_fma_f32 v[52:53], v[52:53], v[72:73], v[112:113] op_sel_hi:[1,0,1] neg_lo:[0,0,1] neg_hi:[0,0,1]
	v_lshlrev_b32_e32 v112, 16, v162
	v_rcp_f32_e32 v101, v73
	v_pk_fma_f32 v[54:55], v[54:55], v[72:73], v[116:117] op_sel_hi:[1,0,1] neg_lo:[0,0,1] neg_hi:[0,0,1]
	v_mul_f32_e32 v73, 0xbfb8aa3b, v112
	v_exp_f32_e32 v73, v73
	v_and_b32_e32 v113, 0xffff0000, v162
	v_pk_mul_f32 v[156:157], v[52:53], v[52:53]
	v_pk_mul_f32 v[102:103], v[100:101], v[48:49]
	v_add_f32_e32 v73, 1.0, v73
	v_rcp_f32_e32 v116, v73
	v_mul_f32_e32 v73, 0xbfb8aa3b, v113
	v_exp_f32_e32 v73, v73
	v_lshl_add_u64 v[100:101], v[154:155], 0, v[192:193]
	v_pk_mul_f32 v[154:155], v[54:55], v[54:55]
	v_lshl_add_u64 v[48:49], v[100:101], 0, s[0:1]
	v_add_f32_e32 v73, 1.0, v73
	v_rcp_f32_e32 v117, v73
	s_mov_b32 s0, 0x800000
	v_pk_mul_f32 v[112:113], v[116:117], v[112:113]
	v_lshlrev_b32_e32 v116, 16, v163
	v_mul_f32_e32 v73, 0xbfb8aa3b, v116
	v_exp_f32_e32 v73, v73
	v_and_b32_e32 v117, 0xffff0000, v163
	v_add_f32_e32 v73, 1.0, v73
	v_rcp_f32_e32 v162, v73
	v_mul_f32_e32 v73, 0xbfb8aa3b, v117
	v_exp_f32_e32 v73, v73
	s_nop 0
	v_add_f32_e32 v73, 1.0, v73
	v_pk_fma_f32 v[56:57], v[56:57], v[72:73], v[118:119] op_sel_hi:[1,0,1] neg_lo:[0,0,1] neg_hi:[0,0,1]
	v_lshlrev_b32_e32 v118, 16, v146
	v_rcp_f32_e32 v163, v73
	v_pk_fma_f32 v[58:59], v[58:59], v[72:73], v[120:121] op_sel_hi:[1,0,1] neg_lo:[0,0,1] neg_hi:[0,0,1]
	v_mul_f32_e32 v73, 0xbfb8aa3b, v118
	v_exp_f32_e32 v73, v73
	v_and_b32_e32 v119, 0xffff0000, v146
	v_pk_mul_f32 v[166:167], v[56:57], v[56:57]
	v_pk_mul_f32 v[116:117], v[162:163], v[116:117]
	v_add_f32_e32 v73, 1.0, v73
	v_rcp_f32_e32 v120, v73
	v_mul_f32_e32 v73, 0xbfb8aa3b, v119
	v_exp_f32_e32 v73, v73
	v_pk_mul_f32 v[162:163], v[58:59], v[58:59]
	v_add_f32_e32 v73, 1.0, v73
	v_rcp_f32_e32 v121, v73
	s_nop 0
	v_pk_mul_f32 v[118:119], v[120:121], v[118:119]
	v_lshlrev_b32_e32 v120, 16, v147
	v_mul_f32_e32 v73, 0xbfb8aa3b, v120
	v_exp_f32_e32 v73, v73
	v_and_b32_e32 v121, 0xffff0000, v147
	v_add_f32_e32 v73, 1.0, v73
	v_rcp_f32_e32 v146, v73
	v_mul_f32_e32 v73, 0xbfb8aa3b, v121
	v_exp_f32_e32 v73, v73
	s_nop 0
	v_add_f32_e32 v73, 1.0, v73
	v_pk_fma_f32 v[60:61], v[60:61], v[72:73], v[122:123] op_sel_hi:[1,0,1] neg_lo:[0,0,1] neg_hi:[0,0,1]
	v_lshlrev_b32_e32 v122, 16, v136
	v_rcp_f32_e32 v147, v73
	v_pk_fma_f32 v[62:63], v[62:63], v[72:73], v[126:127] op_sel_hi:[1,0,1] neg_lo:[0,0,1] neg_hi:[0,0,1]
	v_mul_f32_e32 v73, 0xbfb8aa3b, v122
	v_exp_f32_e32 v73, v73
	v_and_b32_e32 v123, 0xffff0000, v136
	v_pk_mul_f32 v[120:121], v[146:147], v[120:121]
	v_pk_mul_f32 v[172:173], v[60:61], v[60:61]
	v_add_f32_e32 v73, 1.0, v73
	v_rcp_f32_e32 v126, v73
	v_mul_f32_e32 v73, 0xbfb8aa3b, v123
	v_exp_f32_e32 v73, v73
	v_pk_mul_f32 v[170:171], v[62:63], v[62:63]
	v_add_f32_e32 v73, 1.0, v73
	v_rcp_f32_e32 v127, v73
	s_nop 0
	v_pk_mul_f32 v[122:123], v[126:127], v[122:123]
	v_lshlrev_b32_e32 v126, 16, v137
	v_mul_f32_e32 v73, 0xbfb8aa3b, v126
	v_exp_f32_e32 v73, v73
	v_and_b32_e32 v127, 0xffff0000, v137
	v_add_f32_e32 v73, 1.0, v73
	v_rcp_f32_e32 v136, v73
	v_mul_f32_e32 v73, 0xbfb8aa3b, v127
	v_exp_f32_e32 v73, v73
	s_nop 0
	v_add_f32_e32 v73, 1.0, v73
	v_rcp_f32_e32 v137, v73
	v_pk_fma_f32 v[124:125], v[34:35], v[72:73], v[124:125] op_sel_hi:[1,0,1] neg_lo:[0,0,1] neg_hi:[0,0,1]
	v_pk_mul_f32 v[34:35], v[160:161], v[128:129]
	v_pk_mul_f32 v[176:177], v[124:125], v[124:125]
	v_pk_mul_f32 v[126:127], v[136:137], v[126:127]
	v_pk_fma_f32 v[136:137], v[32:33], v[72:73], v[34:35] op_sel_hi:[1,0,1] neg_lo:[0,0,1] neg_hi:[0,0,1]
	v_lshlrev_b32_e32 v32, 16, v182
	v_and_b32_e32 v33, 0xffff0000, v182
	v_mul_f32_e32 v34, 0xbfb8aa3b, v32
	v_mul_f32_e32 v35, 0xbfb8aa3b, v33
	v_exp_f32_e32 v34, v34
	v_exp_f32_e32 v35, v35
	v_pk_mul_f32 v[178:179], v[136:137], v[136:137]
	v_add_f32_e32 v34, 1.0, v34
	v_add_f32_e32 v35, 1.0, v35
	v_rcp_f32_e32 v34, v34
	v_rcp_f32_e32 v35, v35
	s_nop 0
	v_pk_mul_f32 v[146:147], v[34:35], v[32:33]
	v_lshlrev_b32_e32 v32, 16, v183
	v_and_b32_e32 v33, 0xffff0000, v183
	v_mul_f32_e32 v34, 0xbfb8aa3b, v32
	v_mul_f32_e32 v35, 0xbfb8aa3b, v33
	v_exp_f32_e32 v34, v34
	v_exp_f32_e32 v35, v35
	v_add_f32_e32 v34, 1.0, v34
	v_add_f32_e32 v35, 1.0, v35
	v_rcp_f32_e32 v34, v34
	v_rcp_f32_e32 v35, v35
	s_nop 0
	v_pk_mul_f32 v[128:129], v[34:35], v[32:33]
	v_pk_mul_f32 v[34:35], v[160:161], v[130:131]
	v_pk_mul_f32 v[32:33], v[160:161], v[138:139]
	v_pk_fma_f32 v[130:131], v[36:37], v[72:73], v[34:35] op_sel_hi:[1,0,1] neg_lo:[0,0,1] neg_hi:[0,0,1]
	v_lshlrev_b32_e32 v34, 16, v188
	v_and_b32_e32 v35, 0xffff0000, v188
	v_mul_f32_e32 v36, 0xbfb8aa3b, v34
	v_mul_f32_e32 v37, 0xbfb8aa3b, v35
	v_exp_f32_e32 v36, v36
	v_exp_f32_e32 v37, v37
	v_pk_fma_f32 v[32:33], v[38:39], v[72:73], v[32:33] op_sel_hi:[1,0,1] neg_lo:[0,0,1] neg_hi:[0,0,1]
	v_pk_mul_f32 v[184:185], v[130:131], v[130:131]
	v_add_f32_e32 v36, 1.0, v36
	v_add_f32_e32 v37, 1.0, v37
	v_rcp_f32_e32 v36, v36
	v_rcp_f32_e32 v37, v37
	v_pk_mul_f32 v[182:183], v[32:33], v[32:33]
	v_pk_mul_f32 v[138:139], v[36:37], v[34:35]
	v_lshlrev_b32_e32 v34, 16, v189
	v_and_b32_e32 v35, 0xffff0000, v189
	v_mul_f32_e32 v36, 0xbfb8aa3b, v34
	v_mul_f32_e32 v37, 0xbfb8aa3b, v35
	v_exp_f32_e32 v36, v36
	v_exp_f32_e32 v37, v37
	v_add_f32_e32 v36, 1.0, v36
	v_add_f32_e32 v37, 1.0, v37
	v_rcp_f32_e32 v36, v36
	v_rcp_f32_e32 v37, v37
	s_nop 0
	v_pk_mul_f32 v[38:39], v[36:37], v[34:35]
	v_pk_mul_f32 v[36:37], v[160:161], v[132:133]
	v_pk_mul_f32 v[34:35], v[160:161], v[144:145]
	v_pk_fma_f32 v[132:133], v[40:41], v[72:73], v[36:37] op_sel_hi:[1,0,1] neg_lo:[0,0,1] neg_hi:[0,0,1]
	v_lshlrev_b32_e32 v36, 16, v186
	v_and_b32_e32 v37, 0xffff0000, v186
	v_mul_f32_e32 v40, 0xbfb8aa3b, v36
	v_mul_f32_e32 v41, 0xbfb8aa3b, v37
	v_exp_f32_e32 v40, v40
	v_exp_f32_e32 v41, v41
	v_pk_fma_f32 v[34:35], v[42:43], v[72:73], v[34:35] op_sel_hi:[1,0,1] neg_lo:[0,0,1] neg_hi:[0,0,1]
	v_pk_mul_f32 v[42:43], v[160:161], v[148:149]
	v_add_f32_e32 v40, 1.0, v40
	v_add_f32_e32 v41, 1.0, v41
	v_rcp_f32_e32 v40, v40
	v_rcp_f32_e32 v41, v41
	v_pk_mul_f32 v[190:191], v[132:133], v[132:133]
	v_pk_mul_f32 v[188:189], v[34:35], v[34:35]
	v_pk_mul_f32 v[144:145], v[40:41], v[36:37]
	v_lshlrev_b32_e32 v36, 16, v187
	v_and_b32_e32 v37, 0xffff0000, v187
	v_mul_f32_e32 v40, 0xbfb8aa3b, v36
	v_mul_f32_e32 v41, 0xbfb8aa3b, v37
	v_exp_f32_e32 v40, v40
	v_exp_f32_e32 v41, v41
	v_add_f32_e32 v40, 1.0, v40
	v_add_f32_e32 v41, 1.0, v41
	v_rcp_f32_e32 v40, v40
	v_rcp_f32_e32 v41, v41
	s_nop 0
	v_pk_mul_f32 v[40:41], v[40:41], v[36:37]
	v_pk_mul_f32 v[36:37], v[160:161], v[164:165]
	s_nop 0
	v_pk_fma_f32 v[36:37], v[46:47], v[72:73], v[36:37] op_sel_hi:[1,0,1] neg_lo:[0,0,1] neg_hi:[0,0,1]
	v_pk_fma_f32 v[46:47], v[44:45], v[72:73], v[42:43] op_sel_hi:[1,0,1] neg_lo:[0,0,1] neg_hi:[0,0,1]
	v_lshlrev_b32_e32 v42, 16, v180
	v_and_b32_e32 v43, 0xffff0000, v180
	v_mul_f32_e32 v44, 0xbfb8aa3b, v42
	v_mul_f32_e32 v45, 0xbfb8aa3b, v43
	v_exp_f32_e32 v44, v44
	v_exp_f32_e32 v45, v45
	v_pk_mul_f32 v[186:187], v[46:47], v[46:47]
	v_pk_mul_f32 v[164:165], v[36:37], v[36:37]
	v_add_f32_e32 v44, 1.0, v44
	v_add_f32_e32 v45, 1.0, v45
	v_rcp_f32_e32 v44, v44
	v_rcp_f32_e32 v45, v45
	s_nop 0
	v_pk_mul_f32 v[148:149], v[44:45], v[42:43]
	v_lshlrev_b32_e32 v42, 16, v181
	v_and_b32_e32 v43, 0xffff0000, v181
	v_mul_f32_e32 v44, 0xbfb8aa3b, v42
	v_mul_f32_e32 v45, 0xbfb8aa3b, v43
	v_exp_f32_e32 v44, v44
	v_exp_f32_e32 v45, v45
	v_add_f32_e32 v44, 1.0, v44
	v_add_f32_e32 v45, 1.0, v45
	v_rcp_f32_e32 v44, v44
	v_rcp_f32_e32 v45, v45
	s_nop 0
	v_pk_mul_f32 v[42:43], v[44:45], v[42:43]
	v_pk_mul_f32 v[44:45], v[160:161], v[150:151]
	s_nop 0
	v_pk_fma_f32 v[18:19], v[18:19], v[72:73], v[44:45] op_sel_hi:[1,0,1] neg_lo:[0,0,1] neg_hi:[0,0,1]
	v_pk_mul_f32 v[44:45], v[160:161], v[140:141]
	v_pk_mul_f32 v[180:181], v[18:19], v[18:19]
	v_pk_fma_f32 v[140:141], v[16:17], v[72:73], v[44:45] op_sel_hi:[1,0,1] neg_lo:[0,0,1] neg_hi:[0,0,1]
	v_lshlrev_b32_e32 v16, 16, v174
	v_and_b32_e32 v17, 0xffff0000, v174
	v_mul_f32_e32 v44, 0xbfb8aa3b, v16
	v_mul_f32_e32 v45, 0xbfb8aa3b, v17
	v_exp_f32_e32 v44, v44
	v_exp_f32_e32 v45, v45
	v_pk_mul_f32 v[194:195], v[140:141], v[140:141]
	v_add_f32_e32 v44, 1.0, v44
	v_add_f32_e32 v45, 1.0, v45
	v_rcp_f32_e32 v44, v44
	v_rcp_f32_e32 v45, v45
	s_nop 0
	v_pk_mul_f32 v[150:151], v[44:45], v[16:17]
	v_lshlrev_b32_e32 v16, 16, v175
	v_and_b32_e32 v17, 0xffff0000, v175
	v_mul_f32_e32 v44, 0xbfb8aa3b, v16
	v_mul_f32_e32 v45, 0xbfb8aa3b, v17
	v_exp_f32_e32 v44, v44
	v_exp_f32_e32 v45, v45
	v_add_f32_e32 v44, 1.0, v44
	v_add_f32_e32 v45, 1.0, v45
	v_rcp_f32_e32 v44, v44
	v_rcp_f32_e32 v45, v45
	s_nop 0
	v_pk_mul_f32 v[44:45], v[44:45], v[16:17]
	v_pk_mul_f32 v[16:17], v[160:161], v[142:143]
	s_nop 0
	v_pk_fma_f32 v[16:17], v[22:23], v[72:73], v[16:17] op_sel_hi:[1,0,1] neg_lo:[0,0,1] neg_hi:[0,0,1]
	v_pk_mul_f32 v[22:23], v[160:161], v[134:135]
	v_pk_mul_f32 v[174:175], v[16:17], v[16:17]
	v_pk_fma_f32 v[134:135], v[20:21], v[72:73], v[22:23] op_sel_hi:[1,0,1] neg_lo:[0,0,1] neg_hi:[0,0,1]
	v_lshlrev_b32_e32 v20, 16, v168
	v_and_b32_e32 v21, 0xffff0000, v168
	v_mul_f32_e32 v22, 0xbfb8aa3b, v20
	v_mul_f32_e32 v23, 0xbfb8aa3b, v21
	v_exp_f32_e32 v22, v22
	v_exp_f32_e32 v23, v23
	v_pk_mul_f32 v[196:197], v[134:135], v[134:135]
	v_add_f32_e32 v22, 1.0, v22
	v_add_f32_e32 v23, 1.0, v23
	v_rcp_f32_e32 v22, v22
	v_rcp_f32_e32 v23, v23
	s_nop 0
	v_pk_mul_f32 v[142:143], v[22:23], v[20:21]
	v_lshlrev_b32_e32 v20, 16, v169
	v_and_b32_e32 v21, 0xffff0000, v169
	v_mul_f32_e32 v22, 0xbfb8aa3b, v20
	v_mul_f32_e32 v23, 0xbfb8aa3b, v21
	v_exp_f32_e32 v22, v22
	v_exp_f32_e32 v23, v23
	v_add_f32_e32 v22, 1.0, v22
	v_add_f32_e32 v23, 1.0, v23
	v_rcp_f32_e32 v22, v22
	v_rcp_f32_e32 v23, v23
	s_nop 0
	v_pk_mul_f32 v[22:23], v[22:23], v[20:21]
	v_pk_mul_f32 v[20:21], v[160:161], v[106:107]
	s_nop 0
	v_pk_fma_f32 v[20:21], v[26:27], v[72:73], v[20:21] op_sel_hi:[1,0,1] neg_lo:[0,0,1] neg_hi:[0,0,1]
	v_pk_mul_f32 v[26:27], v[160:161], v[104:105]
	v_pk_mul_f32 v[168:169], v[20:21], v[20:21]
	v_pk_fma_f32 v[104:105], v[24:25], v[72:73], v[26:27] op_sel_hi:[1,0,1] neg_lo:[0,0,1] neg_hi:[0,0,1]
	v_lshlrev_b32_e32 v24, 16, v158
	v_and_b32_e32 v25, 0xffff0000, v158
	v_mul_f32_e32 v26, 0xbfb8aa3b, v24
	v_mul_f32_e32 v27, 0xbfb8aa3b, v25
	v_exp_f32_e32 v26, v26
	v_exp_f32_e32 v27, v27
	v_pk_mul_f32 v[198:199], v[104:105], v[104:105]
	v_add_f32_e32 v26, 1.0, v26
	v_add_f32_e32 v27, 1.0, v27
	v_rcp_f32_e32 v26, v26
	v_rcp_f32_e32 v27, v27
	s_nop 0
	v_pk_mul_f32 v[106:107], v[26:27], v[24:25]
	v_lshlrev_b32_e32 v24, 16, v159
	v_and_b32_e32 v25, 0xffff0000, v159
	v_mul_f32_e32 v26, 0xbfb8aa3b, v24
	v_mul_f32_e32 v27, 0xbfb8aa3b, v25
	v_exp_f32_e32 v26, v26
	v_exp_f32_e32 v27, v27
	v_add_f32_e32 v26, 1.0, v26
	v_add_f32_e32 v27, 1.0, v27
	v_rcp_f32_e32 v26, v26
	v_rcp_f32_e32 v27, v27
	s_nop 0
	v_pk_mul_f32 v[26:27], v[26:27], v[24:25]
	v_pk_mul_f32 v[24:25], v[160:161], v[92:93]
	s_nop 0
	v_pk_fma_f32 v[24:25], v[30:31], v[72:73], v[24:25] op_sel_hi:[1,0,1] neg_lo:[0,0,1] neg_hi:[0,0,1]
	v_pk_mul_f32 v[30:31], v[160:161], v[90:91]
	v_pk_mul_f32 v[158:159], v[24:25], v[24:25]
	v_pk_fma_f32 v[90:91], v[28:29], v[72:73], v[30:31] op_sel_hi:[1,0,1] neg_lo:[0,0,1] neg_hi:[0,0,1]
	v_lshlrev_b32_e32 v28, 16, v152
	v_and_b32_e32 v29, 0xffff0000, v152
	v_mul_f32_e32 v30, 0xbfb8aa3b, v28
	v_mul_f32_e32 v31, 0xbfb8aa3b, v29
	v_exp_f32_e32 v30, v30
	v_exp_f32_e32 v31, v31
	v_pk_mul_f32 v[200:201], v[90:91], v[90:91]
	v_add_f32_e32 v30, 1.0, v30
	v_add_f32_e32 v31, 1.0, v31
	v_rcp_f32_e32 v30, v30
	v_rcp_f32_e32 v31, v31
	s_nop 0
	v_pk_mul_f32 v[92:93], v[30:31], v[28:29]
	v_lshlrev_b32_e32 v28, 16, v153
	v_and_b32_e32 v29, 0xffff0000, v153
	v_mul_f32_e32 v30, 0xbfb8aa3b, v28
	v_mul_f32_e32 v31, 0xbfb8aa3b, v29
	v_exp_f32_e32 v30, v30
	v_exp_f32_e32 v31, v31
	v_add_f32_e32 v30, 1.0, v30
	v_add_f32_e32 v31, 1.0, v31
	v_rcp_f32_e32 v30, v30
	v_rcp_f32_e32 v31, v31
	s_nop 0
	v_pk_mul_f32 v[28:29], v[30:31], v[28:29]
	v_pk_mul_f32 v[30:31], v[160:161], v[88:89]
	s_nop 0
	v_pk_fma_f32 v[2:3], v[2:3], v[72:73], v[30:31] op_sel_hi:[1,0,1] neg_lo:[0,0,1] neg_hi:[0,0,1]
	v_pk_mul_f32 v[30:31], v[160:161], v[86:87]
	v_pk_mul_f32 v[152:153], v[2:3], v[2:3]
	v_pk_fma_f32 v[86:87], v[0:1], v[72:73], v[30:31] op_sel_hi:[1,0,1] neg_lo:[0,0,1] neg_hi:[0,0,1]
	v_lshlrev_b32_e32 v0, 16, v114
	v_and_b32_e32 v1, 0xffff0000, v114
	v_mul_f32_e32 v30, 0xbfb8aa3b, v0
	v_mul_f32_e32 v31, 0xbfb8aa3b, v1
	v_exp_f32_e32 v30, v30
	v_exp_f32_e32 v31, v31
	v_pk_mul_f32 v[202:203], v[86:87], v[86:87]
	v_add_f32_e32 v30, 1.0, v30
	v_add_f32_e32 v31, 1.0, v31
	v_rcp_f32_e32 v30, v30
	v_rcp_f32_e32 v31, v31
	s_nop 0
	v_pk_mul_f32 v[88:89], v[30:31], v[0:1]
	v_lshlrev_b32_e32 v0, 16, v115
	v_and_b32_e32 v1, 0xffff0000, v115
	v_mul_f32_e32 v30, 0xbfb8aa3b, v0
	v_mul_f32_e32 v31, 0xbfb8aa3b, v1
	v_exp_f32_e32 v30, v30
	v_exp_f32_e32 v31, v31
	v_add_f32_e32 v30, 1.0, v30
	v_add_f32_e32 v31, 1.0, v31
	v_rcp_f32_e32 v30, v30
	v_rcp_f32_e32 v31, v31
	s_nop 0
	v_pk_mul_f32 v[30:31], v[30:31], v[0:1]
	v_pk_mul_f32 v[0:1], v[160:161], v[84:85]
	s_nop 0
	v_pk_fma_f32 v[0:1], v[6:7], v[72:73], v[0:1] op_sel_hi:[1,0,1] neg_lo:[0,0,1] neg_hi:[0,0,1]
	v_pk_mul_f32 v[6:7], v[160:161], v[82:83]
	v_pk_mul_f32 v[84:85], v[0:1], v[0:1]
	v_pk_fma_f32 v[6:7], v[4:5], v[72:73], v[6:7] op_sel_hi:[1,0,1] neg_lo:[0,0,1] neg_hi:[0,0,1]
	v_lshlrev_b32_e32 v4, 16, v94
	v_mul_f32_e32 v73, 0xbfb8aa3b, v4
	v_exp_f32_e32 v73, v73
	v_and_b32_e32 v5, 0xffff0000, v94
	v_pk_mul_f32 v[114:115], v[6:7], v[6:7]
	v_add_f32_e32 v73, 1.0, v73
	v_rcp_f32_e32 v82, v73
	v_mul_f32_e32 v73, 0xbfb8aa3b, v5
	v_exp_f32_e32 v73, v73
	s_nop 0
	v_add_f32_e32 v73, 1.0, v73
	v_rcp_f32_e32 v83, v73
	s_nop 0
	v_pk_mul_f32 v[82:83], v[82:83], v[4:5]
	v_lshlrev_b32_e32 v4, 16, v95
	v_mul_f32_e32 v73, 0xbfb8aa3b, v4
	v_exp_f32_e32 v73, v73
	v_and_b32_e32 v5, 0xffff0000, v95
	v_add_f32_e32 v73, 1.0, v73
	v_rcp_f32_e32 v94, v73
	v_mul_f32_e32 v73, 0xbfb8aa3b, v5
	v_exp_f32_e32 v73, v73
	s_nop 0
	v_add_f32_e32 v73, 1.0, v73
	v_rcp_f32_e32 v95, v73
	v_pk_fma_f32 v[10:11], v[10:11], v[72:73], v[80:81] op_sel_hi:[1,0,1] neg_lo:[0,0,1] neg_hi:[0,0,1]
	v_pk_fma_f32 v[72:73], v[8:9], v[72:73], v[78:79] op_sel_hi:[1,0,1] neg_lo:[0,0,1] neg_hi:[0,0,1]
	v_lshlrev_b32_e32 v78, 16, v70
	v_and_b32_e32 v79, 0xffff0000, v70
	v_mul_f32_e32 v70, 0xbfb8aa3b, v78
	v_exp_f32_e32 v70, v70
	v_pk_mul_f32 v[4:5], v[94:95], v[4:5]
	v_pk_mul_f32 v[8:9], v[72:73], v[72:73]
	v_pk_mul_f32 v[80:81], v[10:11], v[10:11]
	v_add_f32_e32 v70, 1.0, v70
	v_rcp_f32_e32 v94, v70
	v_mul_f32_e32 v70, 0xbfb8aa3b, v79
	v_exp_f32_e32 v70, v70
	s_nop 0
	v_add_f32_e32 v70, 1.0, v70
	v_rcp_f32_e32 v95, v70
	v_add_f32_e32 v70, v110, v111
	v_add_f32_e32 v70, v70, v108
	v_add_f32_e32 v70, v70, v109
	v_add_f32_e32 v70, v70, v156
	v_add_f32_e32 v70, v70, v157
	v_add_f32_e32 v70, v70, v154
	v_add_f32_e32 v70, v70, v155
	v_add_f32_e32 v70, v70, v166
	v_add_f32_e32 v70, v70, v167
	v_add_f32_e32 v70, v70, v162
	v_add_f32_e32 v70, v70, v163
	v_add_f32_e32 v70, v70, v172
	v_add_f32_e32 v70, v70, v173
	v_add_f32_e32 v70, v70, v170
	v_add_f32_e32 v70, v70, v171
	v_add_f32_e32 v70, v70, v178
	v_add_f32_e32 v70, v70, v179
	v_add_f32_e32 v70, v70, v176
	v_add_f32_e32 v70, v70, v177
	v_add_f32_e32 v70, v70, v184
	v_add_f32_e32 v70, v70, v185
	v_add_f32_e32 v70, v70, v182
	v_add_f32_e32 v70, v70, v183
	v_add_f32_e32 v70, v70, v190
	v_add_f32_e32 v70, v70, v191
	v_add_f32_e32 v70, v70, v188
	v_add_f32_e32 v70, v70, v189
	v_add_f32_e32 v70, v70, v186
	v_add_f32_e32 v70, v70, v187
	v_add_f32_e32 v70, v70, v164
	v_add_f32_e32 v70, v70, v165
	v_add_f32_e32 v70, v70, v194
	v_add_f32_e32 v70, v70, v195
	v_add_f32_e32 v70, v70, v180
	v_add_f32_e32 v70, v70, v181
	v_add_f32_e32 v70, v70, v196
	v_add_f32_e32 v70, v70, v197
	v_add_f32_e32 v70, v70, v174
	v_add_f32_e32 v70, v70, v175
	v_add_f32_e32 v70, v70, v198
	v_add_f32_e32 v70, v70, v199
	v_add_f32_e32 v70, v70, v168
	v_add_f32_e32 v70, v70, v169
	v_add_f32_e32 v70, v70, v200
	v_add_f32_e32 v70, v70, v201
	v_add_f32_e32 v70, v70, v158
	v_add_f32_e32 v70, v70, v159
	v_add_f32_e32 v70, v70, v202
	v_add_f32_e32 v70, v70, v203
	v_add_f32_e32 v70, v70, v152
	v_add_f32_e32 v70, v70, v153
	v_add_f32_e32 v70, v70, v114
	v_add_f32_e32 v70, v70, v115
	v_add_f32_e32 v70, v70, v84
	v_add_f32_e32 v70, v70, v85
	v_add_f32_e32 v8, v70, v8
	v_add_f32_e32 v8, v8, v9
	v_add_f32_e32 v8, v8, v80
	v_add_f32_e32 v8, v8, v81
	v_add_f32_e32 v8, v8, v74
	v_add_f32_e32 v8, v8, v75
	v_add_f32_e32 v8, v8, v76
	v_add_f32_e32 v8, v8, v77
	ds_bpermute_b32 v9, v218, v8
	v_pk_mul_f32 v[78:79], v[94:95], v[78:79]
	s_waitcnt lgkmcnt(0)
	v_add_f32_e32 v8, v8, v9
	v_fmamk_f32 v8, v8, 0x3c000000, v207
	v_cmp_gt_f32_e32 vcc, s0, v8
	v_mul_f32_e32 v9, 0x4b800000, v8
	s_brev_b32 s0, 36
	v_cndmask_b32_e32 v8, v8, v9, vcc
	v_rsq_f32_e32 v8, v8
	s_nop 0
	v_mul_f32_e32 v9, 0x45800000, v8
	v_cndmask_b32_e32 v8, v8, v9, vcc
	v_mul_f32_e32 v8, v204, v8
	v_pk_mul_f32 v[74:75], v[96:97], v[8:9] op_sel_hi:[1,0]
	v_pk_mul_f32 v[50:51], v[50:51], v[8:9] op_sel_hi:[1,0]
	v_pk_mul_f32 v[12:13], v[74:75], v[12:13]
	v_pk_mul_f32 v[14:15], v[50:51], v[14:15]
	v_pk_mul_f32 v[12:13], v[98:99], v[12:13]
	v_pk_mul_f32 v[14:15], v[102:103], v[14:15]
	v_cvt_pk_bf16_f32 v12, v12, v13
	v_cvt_pk_bf16_f32 v13, v14, v15
	v_add_co_u32_e32 v14, vcc, s0, v100
	v_pk_mul_f32 v[50:51], v[52:53], v[8:9] op_sel_hi:[1,0]
	s_nop 0
	v_addc_co_u32_e32 v15, vcc, 0, v101, vcc
	flat_store_dwordx2 v[14:15], v[12:13] offset:1024
	global_load_dwordx4 v[252:255], v205, s[10:11] offset:128
	v_pk_mul_f32 v[32:33], v[32:33], v[8:9] op_sel_hi:[1,0]
	v_pk_mul_f32 v[18:19], v[18:19], v[8:9] op_sel_hi:[1,0]
	v_pk_mul_f32 v[16:17], v[16:17], v[8:9] op_sel_hi:[1,0]
	v_pk_mul_f32 v[2:3], v[2:3], v[8:9] op_sel_hi:[1,0]
	v_pk_mul_f32 v[0:1], v[0:1], v[8:9] op_sel_hi:[1,0]
	v_pk_mul_f32 v[10:11], v[10:11], v[8:9] op_sel_hi:[1,0]
	v_pk_mul_f32 v[12:13], v[50:51], v[240:241]
	v_pk_mul_f32 v[50:51], v[54:55], v[8:9] op_sel_hi:[1,0]
	v_pk_mul_f32 v[12:13], v[112:113], v[12:13]
	v_pk_mul_f32 v[14:15], v[50:51], v[242:243]
	v_cvt_pk_bf16_f32 v12, v12, v13
	v_pk_mul_f32 v[14:15], v[116:117], v[14:15]
	v_pk_mul_f32 v[50:51], v[56:57], v[8:9] op_sel_hi:[1,0]
	v_cvt_pk_bf16_f32 v13, v14, v15
	flat_store_dwordx2 v[48:49], v[12:13] offset:16
	global_load_dwordx4 v[240:243], v205, s[10:11] offset:160
	v_pk_mul_f32 v[12:13], v[50:51], v[244:245]
	v_pk_mul_f32 v[50:51], v[58:59], v[8:9] op_sel_hi:[1,0]
	v_pk_mul_f32 v[12:13], v[118:119], v[12:13]
	v_pk_mul_f32 v[14:15], v[50:51], v[246:247]
	v_cvt_pk_bf16_f32 v12, v12, v13
	v_pk_mul_f32 v[14:15], v[120:121], v[14:15]
	v_pk_mul_f32 v[50:51], v[60:61], v[8:9] op_sel_hi:[1,0]
	v_cvt_pk_bf16_f32 v13, v14, v15
	flat_store_dwordx2 v[48:49], v[12:13] offset:32
	global_load_dwordx4 v[244:247], v205, s[10:11] offset:192
	v_pk_mul_f32 v[12:13], v[50:51], v[248:249]
	v_pk_mul_f32 v[50:51], v[62:63], v[8:9] op_sel_hi:[1,0]
	v_pk_mul_f32 v[12:13], v[122:123], v[12:13]
	v_pk_mul_f32 v[14:15], v[50:51], v[250:251]
	v_cvt_pk_bf16_f32 v12, v12, v13
	v_pk_mul_f32 v[14:15], v[126:127], v[14:15]
	v_pk_mul_f32 v[50:51], v[136:137], v[8:9] op_sel_hi:[1,0]
	v_cvt_pk_bf16_f32 v13, v14, v15
	flat_store_dwordx2 v[48:49], v[12:13] offset:48
	global_load_dwordx4 v[248:251], v205, s[10:11] offset:224
	s_waitcnt vmcnt(6)
	v_pk_mul_f32 v[12:13], v[50:51], v[252:253]
	v_pk_mul_f32 v[50:51], v[124:125], v[8:9] op_sel_hi:[1,0]
	v_pk_mul_f32 v[12:13], v[146:147], v[12:13]
	v_pk_mul_f32 v[14:15], v[50:51], v[254:255]
	v_cvt_pk_bf16_f32 v12, v12, v13
	v_pk_mul_f32 v[14:15], v[128:129], v[14:15]
	v_pk_mul_f32 v[50:51], v[130:131], v[8:9] op_sel_hi:[1,0]
	v_cvt_pk_bf16_f32 v13, v14, v15
	flat_store_dwordx2 v[48:49], v[12:13] offset:64
	global_load_dwordx4 v[252:255], v205, s[10:11] offset:256
	s_waitcnt vmcnt(6)
	v_pk_mul_f32 v[12:13], v[50:51], v[240:241]
	v_pk_mul_f32 v[14:15], v[32:33], v[242:243]
	v_pk_mul_f32 v[12:13], v[138:139], v[12:13]
	v_pk_mul_f32 v[14:15], v[38:39], v[14:15]
	v_cvt_pk_bf16_f32 v12, v12, v13
	v_cvt_pk_bf16_f32 v13, v14, v15
	flat_store_dwordx2 v[48:49], v[12:13] offset:80
	global_load_dwordx4 v[240:243], v205, s[10:11] offset:288
	v_pk_mul_f32 v[32:33], v[132:133], v[8:9] op_sel_hi:[1,0]
	s_waitcnt vmcnt(6)
	v_pk_mul_f32 v[12:13], v[32:33], v[244:245]
	v_pk_mul_f32 v[32:33], v[34:35], v[8:9] op_sel_hi:[1,0]
	v_pk_mul_f32 v[12:13], v[144:145], v[12:13]
	v_pk_mul_f32 v[14:15], v[32:33], v[246:247]
	v_cvt_pk_bf16_f32 v12, v12, v13
	v_pk_mul_f32 v[14:15], v[40:41], v[14:15]
	v_pk_mul_f32 v[32:33], v[46:47], v[8:9] op_sel_hi:[1,0]
	v_cvt_pk_bf16_f32 v13, v14, v15
	flat_store_dwordx2 v[48:49], v[12:13] offset:96
	global_load_dwordx4 v[244:247], v205, s[10:11] offset:320
	s_waitcnt vmcnt(6)
	v_pk_mul_f32 v[12:13], v[32:33], v[248:249]
	v_pk_mul_f32 v[32:33], v[36:37], v[8:9] op_sel_hi:[1,0]
	v_pk_mul_f32 v[12:13], v[148:149], v[12:13]
	v_pk_mul_f32 v[14:15], v[32:33], v[250:251]
	v_cvt_pk_bf16_f32 v12, v12, v13
	v_pk_mul_f32 v[14:15], v[42:43], v[14:15]
	v_pk_mul_f32 v[32:33], v[140:141], v[8:9] op_sel_hi:[1,0]
	v_cvt_pk_bf16_f32 v13, v14, v15
	flat_store_dwordx2 v[48:49], v[12:13] offset:112
	global_load_dwordx4 v[248:251], v205, s[10:11] offset:352
	s_waitcnt vmcnt(6)
	v_pk_mul_f32 v[12:13], v[32:33], v[252:253]
	v_pk_mul_f32 v[14:15], v[18:19], v[254:255]
	v_pk_mul_f32 v[12:13], v[150:151], v[12:13]
	v_pk_mul_f32 v[14:15], v[44:45], v[14:15]
	v_cvt_pk_bf16_f32 v12, v12, v13
	v_cvt_pk_bf16_f32 v13, v14, v15
	flat_store_dwordx2 v[48:49], v[12:13] offset:128
	global_load_dwordx4 v[252:255], v205, s[10:11] offset:384
	v_pk_mul_f32 v[18:19], v[134:135], v[8:9] op_sel_hi:[1,0]
	s_waitcnt vmcnt(6)
	v_pk_mul_f32 v[14:15], v[16:17], v[242:243]
	v_pk_mul_f32 v[12:13], v[18:19], v[240:241]
	v_pk_mul_f32 v[14:15], v[22:23], v[14:15]
	v_pk_mul_f32 v[12:13], v[142:143], v[12:13]
	v_pk_mul_f32 v[16:17], v[104:105], v[8:9] op_sel_hi:[1,0]
	v_cvt_pk_bf16_f32 v12, v12, v13
	v_cvt_pk_bf16_f32 v13, v14, v15
	flat_store_dwordx2 v[48:49], v[12:13] offset:144
	global_load_dwordx4 v[240:243], v205, s[10:11] offset:416
	s_waitcnt vmcnt(6)
	v_pk_mul_f32 v[12:13], v[16:17], v[244:245]
	v_pk_mul_f32 v[16:17], v[20:21], v[8:9] op_sel_hi:[1,0]
	v_pk_mul_f32 v[12:13], v[106:107], v[12:13]
	v_pk_mul_f32 v[14:15], v[16:17], v[246:247]
	v_cvt_pk_bf16_f32 v12, v12, v13
	v_pk_mul_f32 v[14:15], v[26:27], v[14:15]
	v_pk_mul_f32 v[16:17], v[90:91], v[8:9] op_sel_hi:[1,0]
	v_cvt_pk_bf16_f32 v13, v14, v15
	flat_store_dwordx2 v[48:49], v[12:13] offset:160
	global_load_dwordx4 v[244:247], v205, s[10:11] offset:448
	s_waitcnt vmcnt(6)
	v_pk_mul_f32 v[12:13], v[16:17], v[248:249]
	v_pk_mul_f32 v[16:17], v[24:25], v[8:9] op_sel_hi:[1,0]
	v_pk_mul_f32 v[12:13], v[92:93], v[12:13]
	v_pk_mul_f32 v[14:15], v[16:17], v[250:251]
	v_cvt_pk_bf16_f32 v12, v12, v13
	v_pk_mul_f32 v[14:15], v[28:29], v[14:15]
	v_pk_mul_f32 v[16:17], v[86:87], v[8:9] op_sel_hi:[1,0]
	v_cvt_pk_bf16_f32 v13, v14, v15
	flat_store_dwordx2 v[48:49], v[12:13] offset:176
	global_load_dwordx4 v[248:251], v205, s[10:11] offset:480
	s_waitcnt vmcnt(6)
	v_pk_mul_f32 v[12:13], v[16:17], v[252:253]
	v_pk_mul_f32 v[2:3], v[2:3], v[254:255]
	v_pk_mul_f32 v[12:13], v[88:89], v[12:13]
	v_pk_mul_f32 v[2:3], v[30:31], v[2:3]
	v_cvt_pk_bf16_f32 v12, v12, v13
	v_cvt_pk_bf16_f32 v13, v2, v3
	flat_store_dwordx2 v[48:49], v[12:13] offset:192
	v_pk_mul_f32 v[2:3], v[6:7], v[8:9] op_sel_hi:[1,0]
	s_waitcnt vmcnt(5)
	v_pk_mul_f32 v[0:1], v[0:1], v[242:243]
	v_pk_mul_f32 v[2:3], v[2:3], v[240:241]
	v_pk_mul_f32 v[0:1], v[4:5], v[0:1]
	v_pk_mul_f32 v[2:3], v[82:83], v[2:3]
	v_pk_mul_f32 v[4:5], v[72:73], v[8:9] op_sel_hi:[1,0]
	v_cvt_pk_bf16_f32 v2, v2, v3
	v_cvt_pk_bf16_f32 v3, v0, v1
	flat_store_dwordx2 v[48:49], v[2:3] offset:208
	s_waitcnt vmcnt(4)
	v_pk_mul_f32 v[0:1], v[4:5], v[244:245]
	s_nop 0
	v_pk_mul_f32 v[0:1], v[78:79], v[0:1]
	v_lshlrev_b32_e32 v4, 16, v71
	v_cvt_pk_bf16_f32 v0, v0, v1
	v_mul_f32_e32 v1, 0xbfb8aa3b, v4
	v_exp_f32_e32 v1, v1
	v_and_b32_e32 v5, 0xffff0000, v71
	v_pk_mul_f32 v[2:3], v[10:11], v[246:247]
	v_pk_mul_f32 v[10:11], v[66:67], v[8:9] op_sel_hi:[1,0]
	v_add_f32_e32 v1, 1.0, v1
	v_rcp_f32_e32 v6, v1
	v_mul_f32_e32 v1, 0xbfb8aa3b, v5
	v_exp_f32_e32 v1, v1
	v_pk_mul_f32 v[8:9], v[64:65], v[8:9] op_sel_hi:[1,0]
	v_add_f32_e32 v1, 1.0, v1
	v_rcp_f32_e32 v7, v1
	s_nop 0
	v_pk_mul_f32 v[4:5], v[6:7], v[4:5]
	s_nop 0
	v_pk_mul_f32 v[2:3], v[4:5], v[2:3]
	v_lshlrev_b32_e32 v4, 16, v68
	v_cvt_pk_bf16_f32 v1, v2, v3
	flat_store_dwordx2 v[48:49], v[0:1] offset:224
	v_and_b32_e32 v5, 0xffff0000, v68
	v_mul_f32_e32 v6, 0xbfb8aa3b, v4
	v_mul_f32_e32 v7, 0xbfb8aa3b, v5
	v_exp_f32_e32 v6, v6
	v_exp_f32_e32 v7, v7
	v_add_f32_e32 v6, 1.0, v6
	v_add_f32_e32 v7, 1.0, v7
	v_rcp_f32_e32 v6, v6
	v_rcp_f32_e32 v7, v7
	s_waitcnt vmcnt(3)
	v_pk_mul_f32 v[0:1], v[10:11], v[248:249]
	v_pk_mul_f32 v[4:5], v[6:7], v[4:5]
	v_pk_mul_f32 v[2:3], v[8:9], v[250:251]
	v_pk_mul_f32 v[0:1], v[4:5], v[0:1]
	v_lshlrev_b32_e32 v4, 16, v69
	v_cvt_pk_bf16_f32 v0, v0, v1
	v_mul_f32_e32 v1, 0xbfb8aa3b, v4
	v_exp_f32_e32 v1, v1
	v_and_b32_e32 v5, 0xffff0000, v69
	v_add_f32_e32 v1, 1.0, v1
	v_rcp_f32_e32 v6, v1
	v_mul_f32_e32 v1, 0xbfb8aa3b, v5
	v_exp_f32_e32 v1, v1
	s_nop 0
	v_add_f32_e32 v1, 1.0, v1
	v_rcp_f32_e32 v7, v1
	s_nop 0
	v_pk_mul_f32 v[4:5], v[6:7], v[4:5]
	s_nop 0
	v_pk_mul_f32 v[2:3], v[4:5], v[2:3]
	s_nop 0
	v_cvt_pk_bf16_f32 v1, v2, v3
	flat_store_dwordx2 v[48:49], v[0:1] offset:240
	s_branch .LBB0_924
